# speedup vs baseline: 1.0427x; 1.0042x over previous
; #define G_STAGE(bufoff, gbase) do { _Pragma("unroll") for (int _i = 0; _i < 2; ++_i) \
;     __builtin_amdgcn_global_load_lds((const unsigned*)((const char*)(gbase) + voffA[_i]), (LAS unsigned*)(lds + (bufoff) + ldsw + _i * 8192), 16, 0, 0); } while (0)
; #define G_LDA(dst, b, h) do { _Pragma("unroll") for (int m = 0; m < 4; ++m) _Pragma("unroll") for (int k = 0; k < 2; ++k) dst[m][k] = *(const LAS bf16x8*)(lds + G_SA(b, h) + aoff + m * 2048 + k * 1024); } while (0)
; #define G_LDB(dst, b, h) do { _Pragma("unroll") for (int n = 0; n < 2; ++n) _Pragma("unroll") for (int k = 0; k < 2; ++k) dst[n][k] = *(const LAS bf16x8*)(lds + G_SB(b, h) + boff + n * 2048 + k * 1024); } while (0)
; #define G_WAIT_V(n) asm volatile("s_waitcnt vmcnt(" #n ")" ::: "memory")
; #define G_WAIT_L(n) asm volatile("s_waitcnt lgkmcnt(" #n ")" ::: "memory")
; #define G_BAR __builtin_amdgcn_s_barrier()
; #define G_SCHED __builtin_amdgcn_sched_barrier(0)
; template <int MODE>
; __device__ __forceinline__ void gemm_phase(const Params& p, int layer, char* lds_generic) {
;     ...
;     for (int t = 0; t < nt; t += 2) {
;       const bool last = (t == nt - 2);
;       const char* a1 = cA + (size_t)(t + 1) * kstep;
;       const char* a2 = last ? nA : cA + (size_t)(t + 2) * kstep; const char* b2 = last ? nB : cB + (size_t)(t + 2) * kstep;
;       const char* a3 = a2 + kstep; const char* b3 = b2 + kstep;
;       G_LDB(B0, 0, 0); G_SCHED; G_LDA(At, 0, 0); G_STAGE(G_SA(1, 1), a1 + hstep);
;       G_WAIT_L(8); G_BAR; G_WAIT_L(0); G_MMA(0, 0, At, B0); G_BAR; G_SCHED;
;       G_LDB(B1, 0, 1); G_STAGE(G_SB(0, 0), b2);
;       G_BAR; G_WAIT_L(0); G_MMA(0, 1, At, B1); G_BAR;
;       G_LDA(At, 0, 1); G_STAGE(G_SA(0, 0), a2);
;       G_BAR; G_WAIT_L(0); G_MMA(1, 0, At, B0); G_BAR; G_SCHED;
;       G_STAGE(G_SB(0, 1), b2 + hstep);
;       G_WAIT_V(6); G_BAR; G_MMA(1, 1, At, B1); G_BAR;
;       G_LDB(B0, 1, 0); G_SCHED; G_LDA(At, 1, 0); G_STAGE(G_SA(0, 1), a2 + hstep);
;       G_WAIT_L(8); G_BAR; G_WAIT_L(0); G_MMA(0, 0, At, B0); G_BAR; G_SCHED;
;       G_LDB(B1, 1, 1); G_STAGE(G_SB(1, 0), b3);
;       G_BAR; G_WAIT_L(0); G_MMA(0, 1, At, B1); G_BAR;
;       G_LDA(At, 1, 1); G_STAGE(G_SA(1, 0), a3);
;       G_BAR; G_WAIT_L(0); G_MMA(1, 0, At, B0); G_BAR; G_SCHED;
;       G_STAGE(G_SB(1, 1), b3 + hstep);
;       G_WAIT_V(6); G_BAR; G_MMA(1, 1, At, B1); G_BAR;
.LBB0_88:
	ds_read_b128 v[156:159], v139
	ds_read_b128 v[160:163], v140
	ds_read_b128 v[164:167], v141
	ds_read_b128 v[168:171], v142
	s_add_u32 s12, s78, 0xfff80080
	s_addc_u32 s13, s79, -1
	s_cmp_eq_u32 s9, 28
	s_cselect_b32 s87, s67, s13
	s_cselect_b32 s86, vcc_lo, s12
	s_cselect_b32 s75, s69, s8
	s_cselect_b32 s74, vcc_hi, s5
	s_mov_b32 m0, s33
	v_lshl_add_u64 v[134:135], s[78:79], 0, v[130:131]
	ds_read_b128 v[172:175], v137
	ds_read_b128 v[176:179], v137 offset:1024
	ds_read_b128 v[180:183], v137 offset:2048
	ds_read_b128 v[184:187], v137 offset:3072
	ds_read_b128 v[188:191], v137 offset:4096
	ds_read_b128 v[194:197], v137 offset:5120
	ds_read_b128 v[198:201], v137 offset:6144
	ds_read_b128 v[202:205], v137 offset:7168
	global_load_lds_dwordx4 v[134:135], off
	v_lshl_add_u64 v[134:135], s[78:79], 0, v[132:133]
	s_mov_b32 m0, s1
	s_nop 0
	global_load_lds_dwordx4 v[134:135], off
	s_waitcnt lgkmcnt(8)
	s_barrier
	s_waitcnt lgkmcnt(0)
	s_waitcnt lgkmcnt(0)
	v_mfma_f32_16x16x32_bf16 v[124:127], v[156:159], v[172:175], v[124:127]
	v_mfma_f32_16x16x32_bf16 v[120:123], v[164:167], v[172:175], v[120:123]
	v_mfma_f32_16x16x32_bf16 v[116:119], v[156:159], v[180:183], v[116:119]
	v_mfma_f32_16x16x32_bf16 v[108:111], v[164:167], v[180:183], v[108:111]
	v_mfma_f32_16x16x32_bf16 v[100:103], v[156:159], v[188:191], v[100:103]
	v_mfma_f32_16x16x32_bf16 v[92:95], v[164:167], v[188:191], v[92:95]
	v_mfma_f32_16x16x32_bf16 v[84:87], v[156:159], v[198:201], v[84:87]
	v_mfma_f32_16x16x32_bf16 v[76:79], v[164:167], v[198:201], v[76:79]
	v_mfma_f32_16x16x32_bf16 v[124:127], v[160:163], v[176:179], v[124:127]
	v_mfma_f32_16x16x32_bf16 v[120:123], v[168:171], v[176:179], v[120:123]
	v_mfma_f32_16x16x32_bf16 v[116:119], v[160:163], v[184:187], v[116:119]
	v_mfma_f32_16x16x32_bf16 v[108:111], v[168:171], v[184:187], v[108:111]
	v_mfma_f32_16x16x32_bf16 v[100:103], v[160:163], v[194:197], v[100:103]
	v_mfma_f32_16x16x32_bf16 v[92:95], v[168:171], v[194:197], v[92:95]
	v_mfma_f32_16x16x32_bf16 v[84:87], v[160:163], v[202:205], v[84:87]
	v_mfma_f32_16x16x32_bf16 v[76:79], v[168:171], v[202:205], v[76:79]
	s_barrier
	s_mov_b32 m0, s34
	v_lshl_add_u64 v[134:135], s[74:75], 0, v[192:193]
	ds_read_b128 v[206:209], v143
	ds_read_b128 v[216:219], v144
	ds_read_b128 v[222:225], v145
	ds_read_b128 v[228:231], v146
	global_load_lds_dwordx4 v[134:135], off
	v_lshl_add_u64 v[210:211], s[74:75], 0, v[128:129]
	s_mov_b32 m0, s35
	s_nop 0
	global_load_lds_dwordx4 v[210:211], off
	s_barrier
	s_waitcnt lgkmcnt(0)
	s_waitcnt lgkmcnt(0)
	v_mfma_f32_16x16x32_bf16 v[112:115], v[206:209], v[172:175], v[112:115]
	v_mfma_f32_16x16x32_bf16 v[104:107], v[222:225], v[172:175], v[104:107]
	v_mfma_f32_16x16x32_bf16 v[96:99], v[206:209], v[180:183], v[96:99]
	v_mfma_f32_16x16x32_bf16 v[88:91], v[222:225], v[180:183], v[88:91]
	v_mfma_f32_16x16x32_bf16 v[80:83], v[206:209], v[188:191], v[80:83]
	v_mfma_f32_16x16x32_bf16 v[72:75], v[222:225], v[188:191], v[72:75]
	v_mfma_f32_16x16x32_bf16 v[68:71], v[206:209], v[198:201], v[68:71]
	v_mfma_f32_16x16x32_bf16 v[64:67], v[222:225], v[198:201], v[64:67]
	v_mfma_f32_16x16x32_bf16 v[112:115], v[216:219], v[176:179], v[112:115]
	v_mfma_f32_16x16x32_bf16 v[104:107], v[228:231], v[176:179], v[104:107]
	v_mfma_f32_16x16x32_bf16 v[96:99], v[216:219], v[184:187], v[96:99]
	v_mfma_f32_16x16x32_bf16 v[88:91], v[228:231], v[184:187], v[88:91]
	v_mfma_f32_16x16x32_bf16 v[80:83], v[216:219], v[194:197], v[80:83]
	v_mfma_f32_16x16x32_bf16 v[72:75], v[228:231], v[194:197], v[72:75]
	v_mfma_f32_16x16x32_bf16 v[68:71], v[216:219], v[202:205], v[68:71]
	v_mfma_f32_16x16x32_bf16 v[64:67], v[228:231], v[202:205], v[64:67]
	s_mov_b32 m0, s62
	v_lshl_add_u64 v[232:233], s[86:87], 0, v[192:193]
	s_barrier
	ds_read_b128 v[172:175], v137 offset:16384
	ds_read_b128 v[176:179], v137 offset:17408
	ds_read_b128 v[180:183], v137 offset:18432
	ds_read_b128 v[184:187], v137 offset:19456
	ds_read_b128 v[188:191], v137 offset:20480
	ds_read_b128 v[194:197], v137 offset:21504
	ds_read_b128 v[198:201], v137 offset:22528
	ds_read_b128 v[202:205], v137 offset:23552
	global_load_lds_dwordx4 v[232:233], off
	v_lshl_add_u64 v[234:235], s[86:87], 0, v[128:129]
	s_mov_b32 m0, s60
	s_nop 0
	global_load_lds_dwordx4 v[234:235], off
	s_barrier
	s_waitcnt lgkmcnt(0)
	s_waitcnt lgkmcnt(0)
	v_mfma_f32_16x16x32_bf16 v[60:63], v[156:159], v[172:175], v[60:63]
	v_mfma_f32_16x16x32_bf16 v[56:59], v[164:167], v[172:175], v[56:59]
	v_mfma_f32_16x16x32_bf16 v[52:55], v[156:159], v[180:183], v[52:55]
	v_mfma_f32_16x16x32_bf16 v[44:47], v[164:167], v[180:183], v[44:47]
	v_mfma_f32_16x16x32_bf16 v[36:39], v[156:159], v[188:191], v[36:39]
	v_mfma_f32_16x16x32_bf16 v[28:31], v[164:167], v[188:191], v[28:31]
	v_mfma_f32_16x16x32_bf16 v[20:23], v[156:159], v[198:201], v[20:23]
	v_mfma_f32_16x16x32_bf16 v[12:15], v[164:167], v[198:201], v[12:15]
	v_mfma_f32_16x16x32_bf16 v[60:63], v[160:163], v[176:179], v[60:63]
	v_mfma_f32_16x16x32_bf16 v[56:59], v[168:171], v[176:179], v[56:59]
	v_mfma_f32_16x16x32_bf16 v[52:55], v[160:163], v[184:187], v[52:55]
	v_mfma_f32_16x16x32_bf16 v[44:47], v[168:171], v[184:187], v[44:47]
	v_mfma_f32_16x16x32_bf16 v[36:39], v[160:163], v[194:197], v[36:39]
	v_mfma_f32_16x16x32_bf16 v[28:31], v[168:171], v[194:197], v[28:31]
	v_mfma_f32_16x16x32_bf16 v[20:23], v[160:163], v[202:205], v[20:23]
	v_mfma_f32_16x16x32_bf16 v[12:15], v[168:171], v[202:205], v[12:15]
	s_barrier
	s_add_u32 s12, s74, 0x80000
	s_addc_u32 s13, s75, 0
	s_mov_b32 m0, s80
	v_lshl_add_u64 v[156:157], s[12:13], 0, v[192:193]
	global_load_lds_dwordx4 v[156:157], off
	v_lshl_add_u64 v[156:157], s[12:13], 0, v[128:129]
	s_mov_b32 m0, s82
	s_nop 0
	global_load_lds_dwordx4 v[156:157], off
	s_waitcnt vmcnt(6)
	s_barrier
; #define G_STAGE(bufoff, gbase) do { _Pragma("unroll") for (int _i = 0; _i < 2; ++_i) \
;     __builtin_amdgcn_global_load_lds((const unsigned*)((const char*)(gbase) + voffA[_i]), (LAS unsigned*)(lds + (bufoff) + ldsw + _i * 8192), 16, 0, 0); } while (0)
; #define G_LDA(dst, b, h) do { _Pragma("unroll") for (int m = 0; m < 4; ++m) _Pragma("unroll") for (int k = 0; k < 2; ++k) dst[m][k] = *(const LAS bf16x8*)(lds + G_SA(b, h) + aoff + m * 2048 + k * 1024); } while (0)
; #define G_LDB(dst, b, h) do { _Pragma("unroll") for (int n = 0; n < 2; ++n) _Pragma("unroll") for (int k = 0; k < 2; ++k) dst[n][k] = *(const LAS bf16x8*)(lds + G_SB(b, h) + boff + n * 2048 + k * 1024); } while (0)
; #define G_MMA(ai, bj, At, Bt) do { __builtin_amdgcn_s_setprio(1); _Pragma("unroll") for (int m = 0; m < 4; ++m) _Pragma("unroll") for (int n = 0; n < 2; ++n) _Pragma("unroll") for (int k = 0; k < 2; ++k) \
;     acc[ai][bj][m][n] = __builtin_amdgcn_mfma_f32_16x16x32_bf16(Bt[n][k], At[m][k], acc[ai][bj][m][n], 0, 0, 0); __builtin_amdgcn_s_setprio(0); } while (0)
; #define G_WAIT_V(n) asm volatile("s_waitcnt vmcnt(" #n ")" ::: "memory")
; #define G_WAIT_L(n) asm volatile("s_waitcnt lgkmcnt(" #n ")" ::: "memory")
; #define G_BAR __builtin_amdgcn_s_barrier()
; #define G_SCHED __builtin_amdgcn_sched_barrier(0)
; template <int MODE>
; __device__ __forceinline__ void gemm_phase(const Params& p, int layer, char* lds_generic) {
;     ...
;       G_WAIT_V(6); G_BAR; G_MMA(1, 1, At, B1); G_BAR;
;       G_LDB(B0, 1, 0); G_SCHED; G_LDA(At, 1, 0); G_STAGE(G_SA(0, 1), a2 + hstep);
;       G_WAIT_L(8); G_BAR; G_WAIT_L(0); G_MMA(0, 0, At, B0); G_BAR; G_SCHED;
;       G_LDB(B1, 1, 1); G_STAGE(G_SB(1, 0), b3);
;       G_BAR; G_WAIT_L(0); G_MMA(0, 1, At, B1); G_BAR;
;       G_LDA(At, 1, 1); G_STAGE(G_SA(1, 0), a3);
;       G_BAR; G_WAIT_L(0); G_MMA(1, 0, At, B0); G_BAR; G_SCHED;
	v_mfma_f32_16x16x32_bf16 v[48:51], v[206:209], v[172:175], v[48:51]
	v_mfma_f32_16x16x32_bf16 v[40:43], v[222:225], v[172:175], v[40:43]
	v_mfma_f32_16x16x32_bf16 v[32:35], v[206:209], v[180:183], v[32:35]
	v_mfma_f32_16x16x32_bf16 v[24:27], v[222:225], v[180:183], v[24:27]
	v_mfma_f32_16x16x32_bf16 v[16:19], v[206:209], v[188:191], v[16:19]
	v_mfma_f32_16x16x32_bf16 v[8:11], v[222:225], v[188:191], v[8:11]
	v_mfma_f32_16x16x32_bf16 v[4:7], v[206:209], v[198:201], v[4:7]
	v_mfma_f32_16x16x32_bf16 v[0:3], v[222:225], v[198:201], v[0:3]
	v_mfma_f32_16x16x32_bf16 v[48:51], v[216:219], v[176:179], v[48:51]
	v_mfma_f32_16x16x32_bf16 v[40:43], v[228:231], v[176:179], v[40:43]
	v_mfma_f32_16x16x32_bf16 v[32:35], v[216:219], v[184:187], v[32:35]
	v_mfma_f32_16x16x32_bf16 v[24:27], v[228:231], v[184:187], v[24:27]
	v_mfma_f32_16x16x32_bf16 v[16:19], v[216:219], v[194:197], v[16:19]
	v_mfma_f32_16x16x32_bf16 v[8:11], v[228:231], v[194:197], v[8:11]
	v_mfma_f32_16x16x32_bf16 v[4:7], v[216:219], v[202:205], v[4:7]
	v_mfma_f32_16x16x32_bf16 v[0:3], v[228:231], v[202:205], v[0:3]
	s_barrier
	ds_read_b128 v[156:159], v147
	ds_read_b128 v[160:163], v148
	ds_read_b128 v[164:167], v149
	ds_read_b128 v[168:171], v150
	s_add_u32 s12, s86, 0x80000
	s_addc_u32 s13, s87, 0
	s_mov_b32 m0, s83
	v_lshl_add_u64 v[206:207], s[12:13], 0, v[192:193]
	ds_read_b128 v[172:175], v137 offset:32768
	ds_read_b128 v[176:179], v137 offset:33792
	ds_read_b128 v[180:183], v137 offset:34816
	ds_read_b128 v[184:187], v137 offset:35840
	ds_read_b128 v[188:191], v137 offset:36864
	ds_read_b128 v[194:197], v137 offset:37888
	ds_read_b128 v[198:201], v137 offset:38912
	ds_read_b128 v[202:205], v137 offset:39936
	global_load_lds_dwordx4 v[206:207], off
	v_lshl_add_u64 v[206:207], s[12:13], 0, v[128:129]
	s_mov_b32 m0, s84
	s_nop 0
	global_load_lds_dwordx4 v[206:207], off
	s_waitcnt lgkmcnt(8)
	s_barrier
	s_waitcnt lgkmcnt(0)
	s_waitcnt lgkmcnt(0)
	v_mfma_f32_16x16x32_bf16 v[124:127], v[156:159], v[172:175], v[124:127]
	v_mfma_f32_16x16x32_bf16 v[120:123], v[164:167], v[172:175], v[120:123]
	v_mfma_f32_16x16x32_bf16 v[116:119], v[156:159], v[180:183], v[116:119]
	v_mfma_f32_16x16x32_bf16 v[108:111], v[164:167], v[180:183], v[108:111]
	v_mfma_f32_16x16x32_bf16 v[100:103], v[156:159], v[188:191], v[100:103]
	v_mfma_f32_16x16x32_bf16 v[92:95], v[164:167], v[188:191], v[92:95]
	v_mfma_f32_16x16x32_bf16 v[84:87], v[156:159], v[198:201], v[84:87]
	v_mfma_f32_16x16x32_bf16 v[76:79], v[164:167], v[198:201], v[76:79]
	v_mfma_f32_16x16x32_bf16 v[124:127], v[160:163], v[176:179], v[124:127]
	v_mfma_f32_16x16x32_bf16 v[120:123], v[168:171], v[176:179], v[120:123]
	v_mfma_f32_16x16x32_bf16 v[116:119], v[160:163], v[184:187], v[116:119]
	v_mfma_f32_16x16x32_bf16 v[108:111], v[168:171], v[184:187], v[108:111]
	v_mfma_f32_16x16x32_bf16 v[100:103], v[160:163], v[194:197], v[100:103]
	v_mfma_f32_16x16x32_bf16 v[92:95], v[168:171], v[194:197], v[92:95]
	v_mfma_f32_16x16x32_bf16 v[84:87], v[160:163], v[202:205], v[84:87]
	v_mfma_f32_16x16x32_bf16 v[76:79], v[168:171], v[202:205], v[76:79]
	s_barrier
	s_mov_b32 m0, s85
	v_lshl_add_u64 v[134:135], v[134:135], 0, s[90:91]
	ds_read_b128 v[206:209], v151
	ds_read_b128 v[216:219], v152
	ds_read_b128 v[222:225], v153
	ds_read_b128 v[228:231], v154
	global_load_lds_dwordx4 v[134:135], off
	v_lshl_add_u64 v[134:135], v[210:211], 0, s[90:91]
	s_mov_b32 m0, s88
	s_nop 0
	global_load_lds_dwordx4 v[134:135], off
	s_barrier
	s_waitcnt lgkmcnt(0)
	s_waitcnt lgkmcnt(0)
	v_mfma_f32_16x16x32_bf16 v[112:115], v[206:209], v[172:175], v[112:115]
	v_mfma_f32_16x16x32_bf16 v[104:107], v[222:225], v[172:175], v[104:107]
	v_mfma_f32_16x16x32_bf16 v[96:99], v[206:209], v[180:183], v[96:99]
	v_mfma_f32_16x16x32_bf16 v[88:91], v[222:225], v[180:183], v[88:91]
	v_mfma_f32_16x16x32_bf16 v[80:83], v[206:209], v[188:191], v[80:83]
	v_mfma_f32_16x16x32_bf16 v[72:75], v[222:225], v[188:191], v[72:75]
	v_mfma_f32_16x16x32_bf16 v[68:71], v[206:209], v[198:201], v[68:71]
	v_mfma_f32_16x16x32_bf16 v[64:67], v[222:225], v[198:201], v[64:67]
	v_mfma_f32_16x16x32_bf16 v[112:115], v[216:219], v[176:179], v[112:115]
	v_mfma_f32_16x16x32_bf16 v[104:107], v[228:231], v[176:179], v[104:107]
	v_mfma_f32_16x16x32_bf16 v[96:99], v[216:219], v[184:187], v[96:99]
	v_mfma_f32_16x16x32_bf16 v[88:91], v[228:231], v[184:187], v[88:91]
	v_mfma_f32_16x16x32_bf16 v[80:83], v[216:219], v[194:197], v[80:83]
	v_mfma_f32_16x16x32_bf16 v[72:75], v[228:231], v[194:197], v[72:75]
	v_mfma_f32_16x16x32_bf16 v[68:71], v[216:219], v[202:205], v[68:71]
	v_mfma_f32_16x16x32_bf16 v[64:67], v[228:231], v[202:205], v[64:67]
	s_mov_b32 m0, s89
	v_lshl_add_u64 v[134:135], v[232:233], 0, s[90:91]
	s_barrier
	ds_read_b128 v[172:175], v137 offset:49152
	ds_read_b128 v[176:179], v137 offset:50176
	ds_read_b128 v[180:183], v137 offset:51200
	ds_read_b128 v[184:187], v137 offset:52224
	ds_read_b128 v[188:191], v137 offset:53248
	ds_read_b128 v[194:197], v137 offset:54272
	ds_read_b128 v[198:201], v137 offset:55296
	ds_read_b128 v[202:205], v137 offset:56320
	global_load_lds_dwordx4 v[134:135], off
	v_lshl_add_u64 v[134:135], v[234:235], 0, s[90:91]
	s_mov_b32 m0, s92
	s_nop 0
	global_load_lds_dwordx4 v[134:135], off
	s_barrier
; #define G_STAGE(bufoff, gbase) do { _Pragma("unroll") for (int _i = 0; _i < 2; ++_i) \
;     __builtin_amdgcn_global_load_lds((const unsigned*)((const char*)(gbase) + voffA[_i]), (LAS unsigned*)(lds + (bufoff) + ldsw + _i * 8192), 16, 0, 0); } while (0)
; #define G_MMA(ai, bj, At, Bt) do { __builtin_amdgcn_s_setprio(1); _Pragma("unroll") for (int m = 0; m < 4; ++m) _Pragma("unroll") for (int n = 0; n < 2; ++n) _Pragma("unroll") for (int k = 0; k < 2; ++k) \
;     acc[ai][bj][m][n] = __builtin_amdgcn_mfma_f32_16x16x32_bf16(Bt[n][k], At[m][k], acc[ai][bj][m][n], 0, 0, 0); __builtin_amdgcn_s_setprio(0); } while (0)
; #define G_WAIT_V(n) asm volatile("s_waitcnt vmcnt(" #n ")" ::: "memory")
; #define G_WAIT_L(n) asm volatile("s_waitcnt lgkmcnt(" #n ")" ::: "memory")
; #define G_BAR __builtin_amdgcn_s_barrier()
; #define G_SCHED __builtin_amdgcn_sched_barrier(0)
; template <int MODE>
; __device__ __forceinline__ void gemm_phase(const Params& p, int layer, char* lds_generic) {
;     ...
;       G_BAR; G_WAIT_L(0); G_MMA(1, 0, At, B0); G_BAR; G_SCHED;
;       G_STAGE(G_SB(1, 1), b3 + hstep);
;       G_WAIT_V(6); G_BAR; G_MMA(1, 1, At, B1); G_BAR;
;     }
	s_waitcnt lgkmcnt(0)
	s_waitcnt lgkmcnt(0)
	v_mfma_f32_16x16x32_bf16 v[60:63], v[156:159], v[172:175], v[60:63]
	v_mfma_f32_16x16x32_bf16 v[56:59], v[164:167], v[172:175], v[56:59]
	v_mfma_f32_16x16x32_bf16 v[52:55], v[156:159], v[180:183], v[52:55]
	v_mfma_f32_16x16x32_bf16 v[44:47], v[164:167], v[180:183], v[44:47]
	v_mfma_f32_16x16x32_bf16 v[36:39], v[156:159], v[188:191], v[36:39]
	v_mfma_f32_16x16x32_bf16 v[28:31], v[164:167], v[188:191], v[28:31]
	v_mfma_f32_16x16x32_bf16 v[20:23], v[156:159], v[198:201], v[20:23]
	v_mfma_f32_16x16x32_bf16 v[12:15], v[164:167], v[198:201], v[12:15]
	v_mfma_f32_16x16x32_bf16 v[60:63], v[160:163], v[176:179], v[60:63]
	v_mfma_f32_16x16x32_bf16 v[56:59], v[168:171], v[176:179], v[56:59]
	v_mfma_f32_16x16x32_bf16 v[52:55], v[160:163], v[184:187], v[52:55]
	v_mfma_f32_16x16x32_bf16 v[44:47], v[168:171], v[184:187], v[44:47]
	v_mfma_f32_16x16x32_bf16 v[36:39], v[160:163], v[194:197], v[36:39]
	v_mfma_f32_16x16x32_bf16 v[28:31], v[168:171], v[194:197], v[28:31]
	v_mfma_f32_16x16x32_bf16 v[20:23], v[160:163], v[202:205], v[20:23]
	v_mfma_f32_16x16x32_bf16 v[12:15], v[168:171], v[202:205], v[12:15]
	s_barrier
	s_add_u32 s12, s74, 0x80080
	s_addc_u32 s13, s75, 0
	s_mov_b32 m0, s94
	v_lshl_add_u64 v[134:135], s[12:13], 0, v[192:193]
	global_load_lds_dwordx4 v[134:135], off
	v_lshl_add_u64 v[134:135], s[12:13], 0, v[128:129]
	s_mov_b32 m0, s95
	s_nop 0
	global_load_lds_dwordx4 v[134:135], off
	s_waitcnt vmcnt(6)
	s_barrier
	v_mfma_f32_16x16x32_bf16 v[48:51], v[206:209], v[172:175], v[48:51]
	v_mfma_f32_16x16x32_bf16 v[40:43], v[222:225], v[172:175], v[40:43]
	v_mfma_f32_16x16x32_bf16 v[32:35], v[206:209], v[180:183], v[32:35]
	v_mfma_f32_16x16x32_bf16 v[24:27], v[222:225], v[180:183], v[24:27]
	v_mfma_f32_16x16x32_bf16 v[16:19], v[206:209], v[188:191], v[16:19]
	v_mfma_f32_16x16x32_bf16 v[8:11], v[222:225], v[188:191], v[8:11]
	v_mfma_f32_16x16x32_bf16 v[4:7], v[206:209], v[198:201], v[4:7]
	v_mfma_f32_16x16x32_bf16 v[0:3], v[222:225], v[198:201], v[0:3]
	v_mfma_f32_16x16x32_bf16 v[48:51], v[216:219], v[176:179], v[48:51]
	v_mfma_f32_16x16x32_bf16 v[40:43], v[228:231], v[176:179], v[40:43]
	v_mfma_f32_16x16x32_bf16 v[32:35], v[216:219], v[184:187], v[32:35]
	v_mfma_f32_16x16x32_bf16 v[24:27], v[228:231], v[184:187], v[24:27]
	v_mfma_f32_16x16x32_bf16 v[16:19], v[216:219], v[194:197], v[16:19]
	v_mfma_f32_16x16x32_bf16 v[8:11], v[228:231], v[194:197], v[8:11]
	v_mfma_f32_16x16x32_bf16 v[4:7], v[216:219], v[202:205], v[4:7]
	v_mfma_f32_16x16x32_bf16 v[0:3], v[228:231], v[202:205], v[0:3]
	s_add_i32 s9, s9, 2
	s_add_u32 s78, s78, 0x100
	s_addc_u32 s79, s79, 0
	s_add_u32 s5, s5, 0x100
	s_addc_u32 s8, s8, 0
	s_cmp_gt_u32 s9, 29
	s_barrier
	s_cbranch_scc0 .LBB0_88
;   __device__ __forceinline__ float* S() const { return (float*)(ws + 456 * MB); }
; #define G_WAIT_V(n) asm volatile("s_waitcnt vmcnt(" #n ")" ::: "memory")
; #define G_BAR __builtin_amdgcn_s_barrier()
; template <int MODE>
; __device__ __forceinline__ void gemm_epilogue(const Params& p, int layer, const f32x4 (&acc)[2][2][4][2], int pm, int pn, int wr, int wc, int fr, int fq) {
;     ...
;       } else {
; #pragma unroll
;         for (int bj = 0; bj < 2; ++bj) { const int col = pn * 256 + bj * 128 + wc * 32 + 8 * fq; const f32x4 a0 = acc[ai][bj][m][0], a1 = acc[ai][bj][m][1];
;           const u32x4 w = {cvtpk(a0[0], a0[1]), cvtpk(a0[2], a0[3]), cvtpk(a1[0], a1[1]), cvtpk(a1[2], a1[3])};
;           *(u32x4*)((bf16_t*)p.S() + (size_t)row * DM + col) = w; }
;       }
; template <int MODE>
; __device__ __forceinline__ void gemm_phase(const Params& p, int layer, char* lds_generic) {
;     ...
;     gemm_epilogue<MODE>(p, layer, acc, cpm, cpn, wr, wc, fr, fq);
;     if (!has_next) break;
; #pragma unroll
;     for (int a = 0; a < 2; ++a)
; #pragma unroll
;       for (int b = 0; b < 2; ++b)
; #pragma unroll
;         for (int m = 0; m < 4; ++m)
; #pragma unroll
;           for (int n = 0; n < 2; ++n) acc[a][b][m][n] = (f32x4){0.f, 0.f, 0.f, 0.f};
;     cpm = npm; cpn = npn; cA = nA; cB = nB; ++ui;
;   }
;   G_WAIT_V(0);
;   if (wr == 0) G_BAR;
;   G_BAR;
	v_lshl_add_u32 v134, s4, 8, v136
	v_lshl_or_b32 v156, s2, 8, v138
	v_ashrrev_i32_e32 v135, 31, v134
	v_lshlrev_b64 v[158:159], 12, v[134:135]
	v_ashrrev_i32_e32 v157, 31, v156
	v_cvt_pk_bf16_f32 v124, v124, v125
	v_cvt_pk_bf16_f32 v125, v126, v127
	v_cvt_pk_bf16_f32 v126, v120, v121
	v_cvt_pk_bf16_f32 v127, v122, v123
	v_lshl_add_u64 v[122:123], s[6:7], 0, v[158:159]
	v_lshlrev_b64 v[120:121], 1, v[156:157]
	v_lshl_add_u64 v[122:123], v[122:123], 0, v[120:121]
	global_store_dwordx4 v[122:123], v[124:127], off
	v_cvt_pk_bf16_f32 v112, v112, v113
	v_cvt_pk_bf16_f32 v113, v114, v115
	v_cvt_pk_bf16_f32 v114, v104, v105
	v_or_b32_e32 v104, 16, v134
	v_ashrrev_i32_e32 v105, 31, v104
	v_cvt_pk_bf16_f32 v115, v106, v107
	global_store_dwordx4 v[122:123], v[112:115], off offset:256
	s_and_b64 vcc, exec, s[70:71]
	s_mov_b32 s4, s66
	v_lshlrev_b64 v[112:113], 12, v[104:105]
	v_cvt_pk_bf16_f32 v104, v116, v117
	v_cvt_pk_bf16_f32 v105, v118, v119
	v_cvt_pk_bf16_f32 v106, v108, v109
	v_lshl_add_u64 v[108:109], s[6:7], 0, v[112:113]
	v_lshl_add_u64 v[108:109], v[108:109], 0, v[120:121]
	v_cvt_pk_bf16_f32 v107, v110, v111
	global_store_dwordx4 v[108:109], v[104:107], off
	v_cvt_pk_bf16_f32 v96, v96, v97
	v_cvt_pk_bf16_f32 v97, v98, v99
	v_cvt_pk_bf16_f32 v98, v88, v89
	v_or_b32_e32 v88, 32, v134
	v_ashrrev_i32_e32 v89, 31, v88
	v_cvt_pk_bf16_f32 v99, v90, v91
	global_store_dwordx4 v[108:109], v[96:99], off offset:256
	s_mov_b32 s2, s68
	s_mov_b64 s[74:75], s[76:77]
	v_lshlrev_b64 v[96:97], 12, v[88:89]
	v_cvt_pk_bf16_f32 v88, v100, v101
	v_cvt_pk_bf16_f32 v89, v102, v103
	v_cvt_pk_bf16_f32 v90, v92, v93
	v_lshl_add_u64 v[92:93], s[6:7], 0, v[96:97]
	v_lshl_add_u64 v[92:93], v[92:93], 0, v[120:121]
	v_cvt_pk_bf16_f32 v91, v94, v95
	global_store_dwordx4 v[92:93], v[88:91], off
	v_cvt_pk_bf16_f32 v80, v80, v81
	v_cvt_pk_bf16_f32 v81, v82, v83
	v_cvt_pk_bf16_f32 v82, v72, v73
	v_or_b32_e32 v72, 48, v134
	v_ashrrev_i32_e32 v73, 31, v72
	v_cvt_pk_bf16_f32 v83, v74, v75
	global_store_dwordx4 v[92:93], v[80:83], off offset:256
	s_mov_b64 s[78:79], s[72:73]
	s_nop 0
	v_lshlrev_b64 v[80:81], 12, v[72:73]
	v_cvt_pk_bf16_f32 v72, v84, v85
	v_cvt_pk_bf16_f32 v73, v86, v87
	v_cvt_pk_bf16_f32 v74, v76, v77
	v_lshl_add_u64 v[76:77], s[6:7], 0, v[80:81]
	v_lshl_add_u64 v[76:77], v[76:77], 0, v[120:121]
	v_cvt_pk_bf16_f32 v75, v78, v79
	global_store_dwordx4 v[76:77], v[72:75], off
	v_cvt_pk_bf16_f32 v68, v68, v69
	v_cvt_pk_bf16_f32 v69, v70, v71
	v_cvt_pk_bf16_f32 v70, v64, v65
	v_add_u32_e32 v64, 0x80, v134
	v_ashrrev_i32_e32 v65, 31, v64
	v_lshlrev_b64 v[64:65], 12, v[64:65]
	v_cvt_pk_bf16_f32 v71, v66, v67
	global_store_dwordx4 v[76:77], v[68:71], off offset:256
	v_cvt_pk_bf16_f32 v60, v60, v61
	v_cvt_pk_bf16_f32 v61, v62, v63
	v_cvt_pk_bf16_f32 v62, v56, v57
	v_lshl_add_u64 v[56:57], s[6:7], 0, v[64:65]
	v_lshl_add_u64 v[56:57], v[56:57], 0, v[120:121]
	v_cvt_pk_bf16_f32 v63, v58, v59
	global_store_dwordx4 v[56:57], v[60:63], off
	v_cvt_pk_bf16_f32 v48, v48, v49
	v_cvt_pk_bf16_f32 v49, v50, v51
	v_cvt_pk_bf16_f32 v50, v40, v41
	v_add_u32_e32 v40, 0x90, v134
	v_ashrrev_i32_e32 v41, 31, v40
	v_cvt_pk_bf16_f32 v51, v42, v43
	global_store_dwordx4 v[56:57], v[48:51], off offset:256
	s_nop 1
	v_lshlrev_b64 v[48:49], 12, v[40:41]
	v_cvt_pk_bf16_f32 v40, v52, v53
	v_cvt_pk_bf16_f32 v41, v54, v55
	v_cvt_pk_bf16_f32 v42, v44, v45
	v_lshl_add_u64 v[44:45], s[6:7], 0, v[48:49]
	v_lshl_add_u64 v[44:45], v[44:45], 0, v[120:121]
	v_cvt_pk_bf16_f32 v43, v46, v47
	global_store_dwordx4 v[44:45], v[40:43], off
	v_cvt_pk_bf16_f32 v32, v32, v33
	v_cvt_pk_bf16_f32 v33, v34, v35
	v_cvt_pk_bf16_f32 v34, v24, v25
	v_add_u32_e32 v24, 0xa0, v134
	v_ashrrev_i32_e32 v25, 31, v24
	v_cvt_pk_bf16_f32 v35, v26, v27
	global_store_dwordx4 v[44:45], v[32:35], off offset:256
	s_nop 1
	v_lshlrev_b64 v[32:33], 12, v[24:25]
	v_cvt_pk_bf16_f32 v24, v36, v37
	v_cvt_pk_bf16_f32 v25, v38, v39
	v_cvt_pk_bf16_f32 v26, v28, v29
	v_lshl_add_u64 v[28:29], s[6:7], 0, v[32:33]
	v_lshl_add_u64 v[28:29], v[28:29], 0, v[120:121]
	v_cvt_pk_bf16_f32 v27, v30, v31
	global_store_dwordx4 v[28:29], v[24:27], off
	v_cvt_pk_bf16_f32 v16, v16, v17
	v_cvt_pk_bf16_f32 v17, v18, v19
	v_cvt_pk_bf16_f32 v18, v8, v9
	v_add_u32_e32 v8, 0xb0, v134
	v_ashrrev_i32_e32 v9, 31, v8
	v_cvt_pk_bf16_f32 v19, v10, v11
	global_store_dwordx4 v[28:29], v[16:19], off offset:256
	s_nop 1
	v_lshlrev_b64 v[16:17], 12, v[8:9]
	v_cvt_pk_bf16_f32 v8, v20, v21
	v_cvt_pk_bf16_f32 v9, v22, v23
	v_cvt_pk_bf16_f32 v10, v12, v13
	v_lshl_add_u64 v[12:13], s[6:7], 0, v[16:17]
	v_lshl_add_u64 v[12:13], v[12:13], 0, v[120:121]
	v_cvt_pk_bf16_f32 v11, v14, v15
	global_store_dwordx4 v[12:13], v[8:11], off
	v_cvt_pk_bf16_f32 v4, v4, v5
	v_cvt_pk_bf16_f32 v5, v6, v7
	v_cvt_pk_bf16_f32 v6, v0, v1
	v_cvt_pk_bf16_f32 v7, v2, v3
	global_store_dwordx4 v[12:13], v[4:7], off offset:256
	s_cbranch_vccz .LBB0_85
	s_waitcnt vmcnt(0)
	s_cmpk_gt_u32 s16, 0xff
	v_readlane_b32 s92, v254, 32
	s_mov_b32 s88, 0x8000
	s_movk_i32 s89, 0x1400
	s_movk_i32 s66, 0x78
	s_cbranch_scc1 .LBB0_92
	s_barrier

; #define G_STAGE(bufoff, gbase) do { _Pragma("unroll") for (int _i = 0; _i < 2; ++_i) \
;     __builtin_amdgcn_global_load_lds((const unsigned*)((const char*)(gbase) + voffA[_i]), (LAS unsigned*)(lds + (bufoff) + ldsw + _i * 8192), 16, 0, 0); } while (0)
; #define G_LDA(dst, b, h) do { _Pragma("unroll") for (int m = 0; m < 4; ++m) _Pragma("unroll") for (int k = 0; k < 2; ++k) dst[m][k] = *(const LAS bf16x8*)(lds + G_SA(b, h) + aoff + m * 2048 + k * 1024); } while (0)
; #define G_LDB(dst, b, h) do { _Pragma("unroll") for (int n = 0; n < 2; ++n) _Pragma("unroll") for (int k = 0; k < 2; ++k) dst[n][k] = *(const LAS bf16x8*)(lds + G_SB(b, h) + boff + n * 2048 + k * 1024); } while (0)
; #define G_MMA(ai, bj, At, Bt) do { __builtin_amdgcn_s_setprio(1); _Pragma("unroll") for (int m = 0; m < 4; ++m) _Pragma("unroll") for (int n = 0; n < 2; ++n) _Pragma("unroll") for (int k = 0; k < 2; ++k) \
;     acc[ai][bj][m][n] = __builtin_amdgcn_mfma_f32_16x16x32_bf16(Bt[n][k], At[m][k], acc[ai][bj][m][n], 0, 0, 0); __builtin_amdgcn_s_setprio(0); } while (0)
; #define G_WAIT_V(n) asm volatile("s_waitcnt vmcnt(" #n ")" ::: "memory")
; #define G_WAIT_L(n) asm volatile("s_waitcnt lgkmcnt(" #n ")" ::: "memory")
; #define G_BAR __builtin_amdgcn_s_barrier()
; #define G_SCHED __builtin_amdgcn_sched_barrier(0)
; template <int MODE>
; __device__ __forceinline__ void gemm_phase(const Params& p, int layer, char* lds_generic) {
;     ...
;     for (int t = 0; t < nt; t += 2) {
;       const bool last = (t == nt - 2);
;       const char* a1 = cA + (size_t)(t + 1) * kstep;
;       const char* a2 = last ? nA : cA + (size_t)(t + 2) * kstep; const char* b2 = last ? nB : cB + (size_t)(t + 2) * kstep;
;       const char* a3 = a2 + kstep; const char* b3 = b2 + kstep;
;       G_LDB(B0, 0, 0); G_SCHED; G_LDA(At, 0, 0); G_STAGE(G_SA(1, 1), a1 + hstep);
;       G_WAIT_L(8); G_BAR; G_WAIT_L(0); G_MMA(0, 0, At, B0); G_BAR; G_SCHED;
;       G_LDB(B1, 0, 1); G_STAGE(G_SB(0, 0), b2);
;       G_BAR; G_WAIT_L(0); G_MMA(0, 1, At, B1); G_BAR;
;       G_LDA(At, 0, 1); G_STAGE(G_SA(0, 0), a2);
;       G_BAR; G_WAIT_L(0); G_MMA(1, 0, At, B0); G_BAR; G_SCHED;
;       G_STAGE(G_SB(0, 1), b2 + hstep);
;       G_WAIT_V(6); G_BAR; G_MMA(1, 1, At, B1); G_BAR;
;       G_LDB(B0, 1, 0); G_SCHED; G_LDA(At, 1, 0); G_STAGE(G_SA(0, 1), a2 + hstep);
;       G_WAIT_L(8); G_BAR; G_WAIT_L(0); G_MMA(0, 0, At, B0); G_BAR; G_SCHED;
.LBB0_103:
	v_or_b32_e32 v134, 0x10000, v140
	v_add_u32_e32 v142, 0x10400, v140
	v_add_u32_e32 v146, 0x10800, v140
	v_add_u32_e32 v150, 0x10c00, v140
	ds_read_b128 v[134:137], v134
	ds_read_b128 v[142:145], v142
	ds_read_b128 v[146:149], v146
	ds_read_b128 v[150:153], v150
	s_add_u32 s12, vcc_lo, 0xfff80080
	s_addc_u32 s13, vcc_hi, -1
	s_cmp_eq_u32 s9, 28
	s_cselect_b32 s79, s2, s13
	s_cselect_b32 s78, s69, s12
	s_cselect_b32 s77, s71, s60
	s_cselect_b32 s76, s88, s89
	v_lshl_add_u64 v[186:187], vcc, 0, v[130:131]
	s_add_i32 m0, s8, 0xc000
	ds_read_b128 v[154:157], v139
	ds_read_b128 v[158:161], v139 offset:1024
	ds_read_b128 v[162:165], v139 offset:2048
	ds_read_b128 v[166:169], v139 offset:3072
	ds_read_b128 v[170:173], v139 offset:4096
	ds_read_b128 v[174:177], v139 offset:5120
	ds_read_b128 v[178:181], v139 offset:6144
	ds_read_b128 v[182:185], v139 offset:7168
	global_load_lds_dwordx4 v[186:187], off
	v_lshl_add_u64 v[186:187], vcc, 0, v[132:133]
	s_add_i32 m0, s8, 0xe000
	s_nop 0
	global_load_lds_dwordx4 v[186:187], off
	s_waitcnt lgkmcnt(8)
	s_barrier
	s_waitcnt lgkmcnt(0)
	s_waitcnt lgkmcnt(0)
	v_mfma_f32_16x16x32_bf16 v[124:127], v[134:137], v[154:157], v[124:127]
	v_mfma_f32_16x16x32_bf16 v[120:123], v[146:149], v[154:157], v[120:123]
	v_mfma_f32_16x16x32_bf16 v[108:111], v[134:137], v[162:165], v[108:111]
	v_mfma_f32_16x16x32_bf16 v[104:107], v[146:149], v[162:165], v[104:107]
	v_mfma_f32_16x16x32_bf16 v[92:95], v[134:137], v[170:173], v[92:95]
	v_mfma_f32_16x16x32_bf16 v[88:91], v[146:149], v[170:173], v[88:91]
	v_mfma_f32_16x16x32_bf16 v[76:79], v[134:137], v[178:181], v[76:79]
	v_mfma_f32_16x16x32_bf16 v[72:75], v[146:149], v[178:181], v[72:75]
	v_mfma_f32_16x16x32_bf16 v[124:127], v[142:145], v[158:161], v[124:127]
	v_mfma_f32_16x16x32_bf16 v[120:123], v[150:153], v[158:161], v[120:123]
	v_mfma_f32_16x16x32_bf16 v[108:111], v[142:145], v[166:169], v[108:111]
	v_mfma_f32_16x16x32_bf16 v[104:107], v[150:153], v[166:169], v[104:107]
	v_mfma_f32_16x16x32_bf16 v[92:95], v[142:145], v[174:177], v[92:95]
	v_mfma_f32_16x16x32_bf16 v[88:91], v[150:153], v[174:177], v[88:91]
	v_mfma_f32_16x16x32_bf16 v[76:79], v[142:145], v[182:185], v[76:79]
	v_mfma_f32_16x16x32_bf16 v[72:75], v[150:153], v[182:185], v[72:75]
	s_barrier
	v_or_b32_e32 v186, 0x14000, v140
	v_add_u32_e32 v190, 0x14400, v140
	ds_read_b128 v[186:189], v186
	ds_read_b128 v[194:197], v190
	v_add_u32_e32 v190, 0x14800, v140
	v_add_u32_e32 v191, 0x14c00, v140
	s_mov_b32 m0, s92
	ds_read_b128 v[198:201], v190
	ds_read_b128 v[202:205], v191
	v_lshl_add_u64 v[190:191], s[76:77], 0, v[192:193]
	global_load_lds_dwordx4 v[190:191], off
	v_lshl_add_u64 v[206:207], s[76:77], 0, v[128:129]
	s_mov_b32 m0, s94
	s_nop 0
	global_load_lds_dwordx4 v[206:207], off
	s_barrier
	s_waitcnt lgkmcnt(0)
	s_waitcnt lgkmcnt(0)
	v_mfma_f32_16x16x32_bf16 v[116:119], v[186:189], v[154:157], v[116:119]
	v_mfma_f32_16x16x32_bf16 v[112:115], v[198:201], v[154:157], v[112:115]
	v_mfma_f32_16x16x32_bf16 v[100:103], v[186:189], v[162:165], v[100:103]
	v_mfma_f32_16x16x32_bf16 v[96:99], v[198:201], v[162:165], v[96:99]
	v_mfma_f32_16x16x32_bf16 v[84:87], v[186:189], v[170:173], v[84:87]
	v_mfma_f32_16x16x32_bf16 v[80:83], v[198:201], v[170:173], v[80:83]
	v_mfma_f32_16x16x32_bf16 v[68:71], v[186:189], v[178:181], v[68:71]
	v_mfma_f32_16x16x32_bf16 v[64:67], v[198:201], v[178:181], v[64:67]
	v_mfma_f32_16x16x32_bf16 v[116:119], v[194:197], v[158:161], v[116:119]
	v_mfma_f32_16x16x32_bf16 v[112:115], v[202:205], v[158:161], v[112:115]
	v_mfma_f32_16x16x32_bf16 v[100:103], v[194:197], v[166:169], v[100:103]
	v_mfma_f32_16x16x32_bf16 v[96:99], v[202:205], v[166:169], v[96:99]
	v_mfma_f32_16x16x32_bf16 v[84:87], v[194:197], v[174:177], v[84:87]
	v_mfma_f32_16x16x32_bf16 v[80:83], v[202:205], v[174:177], v[80:83]
	v_mfma_f32_16x16x32_bf16 v[68:71], v[194:197], v[182:185], v[68:71]
	v_mfma_f32_16x16x32_bf16 v[64:67], v[202:205], v[182:185], v[64:67]
	s_mov_b32 m0, s8
	v_lshl_add_u64 v[208:209], s[78:79], 0, v[192:193]
	s_barrier
	ds_read_b128 v[154:157], v139 offset:16384
	ds_read_b128 v[158:161], v139 offset:17408
	ds_read_b128 v[162:165], v139 offset:18432
	ds_read_b128 v[166:169], v139 offset:19456
	ds_read_b128 v[170:173], v139 offset:20480
	ds_read_b128 v[174:177], v139 offset:21504
	ds_read_b128 v[178:181], v139 offset:22528
	ds_read_b128 v[182:185], v139 offset:23552
	global_load_lds_dwordx4 v[208:209], off
	v_lshl_add_u64 v[210:211], s[78:79], 0, v[128:129]
	s_mov_b32 m0, s33
	s_nop 0
	global_load_lds_dwordx4 v[210:211], off
	s_barrier
	s_waitcnt lgkmcnt(0)
	s_waitcnt lgkmcnt(0)
	v_mfma_f32_16x16x32_bf16 v[60:63], v[134:137], v[154:157], v[60:63]
	v_mfma_f32_16x16x32_bf16 v[56:59], v[146:149], v[154:157], v[56:59]
	v_mfma_f32_16x16x32_bf16 v[44:47], v[134:137], v[162:165], v[44:47]
	v_mfma_f32_16x16x32_bf16 v[40:43], v[146:149], v[162:165], v[40:43]
	v_mfma_f32_16x16x32_bf16 v[28:31], v[134:137], v[170:173], v[28:31]
	v_mfma_f32_16x16x32_bf16 v[24:27], v[146:149], v[170:173], v[24:27]
	v_mfma_f32_16x16x32_bf16 v[12:15], v[134:137], v[178:181], v[12:15]
	v_mfma_f32_16x16x32_bf16 v[8:11], v[146:149], v[178:181], v[8:11]
	v_mfma_f32_16x16x32_bf16 v[60:63], v[142:145], v[158:161], v[60:63]
	v_mfma_f32_16x16x32_bf16 v[56:59], v[150:153], v[158:161], v[56:59]
	v_mfma_f32_16x16x32_bf16 v[44:47], v[142:145], v[166:169], v[44:47]
	v_mfma_f32_16x16x32_bf16 v[40:43], v[150:153], v[166:169], v[40:43]
	v_mfma_f32_16x16x32_bf16 v[28:31], v[142:145], v[174:177], v[28:31]
	v_mfma_f32_16x16x32_bf16 v[24:27], v[150:153], v[174:177], v[24:27]
	v_mfma_f32_16x16x32_bf16 v[12:15], v[142:145], v[182:185], v[12:15]
	v_mfma_f32_16x16x32_bf16 v[8:11], v[150:153], v[182:185], v[8:11]
	s_barrier
; #define G_STAGE(bufoff, gbase) do { _Pragma("unroll") for (int _i = 0; _i < 2; ++_i) \
;     __builtin_amdgcn_global_load_lds((const unsigned*)((const char*)(gbase) + voffA[_i]), (LAS unsigned*)(lds + (bufoff) + ldsw + _i * 8192), 16, 0, 0); } while (0)
; #define G_LDA(dst, b, h) do { _Pragma("unroll") for (int m = 0; m < 4; ++m) _Pragma("unroll") for (int k = 0; k < 2; ++k) dst[m][k] = *(const LAS bf16x8*)(lds + G_SA(b, h) + aoff + m * 2048 + k * 1024); } while (0)
; #define G_LDB(dst, b, h) do { _Pragma("unroll") for (int n = 0; n < 2; ++n) _Pragma("unroll") for (int k = 0; k < 2; ++k) dst[n][k] = *(const LAS bf16x8*)(lds + G_SB(b, h) + boff + n * 2048 + k * 1024); } while (0)
; #define G_MMA(ai, bj, At, Bt) do { __builtin_amdgcn_s_setprio(1); _Pragma("unroll") for (int m = 0; m < 4; ++m) _Pragma("unroll") for (int n = 0; n < 2; ++n) _Pragma("unroll") for (int k = 0; k < 2; ++k) \
;     acc[ai][bj][m][n] = __builtin_amdgcn_mfma_f32_16x16x32_bf16(Bt[n][k], At[m][k], acc[ai][bj][m][n], 0, 0, 0); __builtin_amdgcn_s_setprio(0); } while (0)
; #define G_WAIT_V(n) asm volatile("s_waitcnt vmcnt(" #n ")" ::: "memory")
; #define G_WAIT_L(n) asm volatile("s_waitcnt lgkmcnt(" #n ")" ::: "memory")
; #define G_BAR __builtin_amdgcn_s_barrier()
; #define G_SCHED __builtin_amdgcn_sched_barrier(0)
; template <int MODE>
; __device__ __forceinline__ void gemm_phase(const Params& p, int layer, char* lds_generic) {
;     ...
;       G_WAIT_V(6); G_BAR; G_MMA(1, 1, At, B1); G_BAR;
;       G_LDB(B0, 1, 0); G_SCHED; G_LDA(At, 1, 0); G_STAGE(G_SA(0, 1), a2 + hstep);
;       G_WAIT_L(8); G_BAR; G_WAIT_L(0); G_MMA(0, 0, At, B0); G_BAR; G_SCHED;
;       G_LDB(B1, 1, 1); G_STAGE(G_SB(1, 0), b3);
;       G_BAR; G_WAIT_L(0); G_MMA(0, 1, At, B1); G_BAR;
;       G_LDA(At, 1, 1); G_STAGE(G_SA(1, 0), a3);
;       G_BAR; G_WAIT_L(0); G_MMA(1, 0, At, B0); G_BAR; G_SCHED;
	s_add_u32 s66, s76, 0x80000
	s_addc_u32 s67, s77, 0
	s_mov_b32 m0, s1
	v_lshl_add_u64 v[134:135], s[66:67], 0, v[192:193]
	global_load_lds_dwordx4 v[134:135], off
	v_lshl_add_u64 v[134:135], s[66:67], 0, v[128:129]
	s_mov_b32 m0, s34
	s_nop 0
	global_load_lds_dwordx4 v[134:135], off
	s_waitcnt vmcnt(6)
	s_barrier
	v_mfma_f32_16x16x32_bf16 v[52:55], v[186:189], v[154:157], v[52:55]
	v_mfma_f32_16x16x32_bf16 v[48:51], v[198:201], v[154:157], v[48:51]
	v_mfma_f32_16x16x32_bf16 v[36:39], v[186:189], v[162:165], v[36:39]
	v_mfma_f32_16x16x32_bf16 v[32:35], v[198:201], v[162:165], v[32:35]
	v_mfma_f32_16x16x32_bf16 v[20:23], v[186:189], v[170:173], v[20:23]
	v_mfma_f32_16x16x32_bf16 v[16:19], v[198:201], v[170:173], v[16:19]
	v_mfma_f32_16x16x32_bf16 v[4:7], v[186:189], v[178:181], v[4:7]
	v_mfma_f32_16x16x32_bf16 v[0:3], v[198:201], v[178:181], v[0:3]
	v_mfma_f32_16x16x32_bf16 v[52:55], v[194:197], v[158:161], v[52:55]
	v_mfma_f32_16x16x32_bf16 v[48:51], v[202:205], v[158:161], v[48:51]
	v_mfma_f32_16x16x32_bf16 v[36:39], v[194:197], v[166:169], v[36:39]
	v_mfma_f32_16x16x32_bf16 v[32:35], v[202:205], v[166:169], v[32:35]
	v_mfma_f32_16x16x32_bf16 v[20:23], v[194:197], v[174:177], v[20:23]
	v_mfma_f32_16x16x32_bf16 v[16:19], v[202:205], v[174:177], v[16:19]
	v_mfma_f32_16x16x32_bf16 v[4:7], v[194:197], v[182:185], v[4:7]
	v_mfma_f32_16x16x32_bf16 v[0:3], v[202:205], v[182:185], v[0:3]
	v_or_b32_e32 v134, 0x18000, v140
	v_add_u32_e32 v142, 0x18400, v140
	v_add_u32_e32 v146, 0x18800, v140
	v_add_u32_e32 v150, 0x18c00, v140
	s_barrier
	ds_read_b128 v[134:137], v134
	ds_read_b128 v[142:145], v142
	ds_read_b128 v[146:149], v146
	ds_read_b128 v[150:153], v150
	s_add_u32 s66, s78, 0x80000
	s_addc_u32 s67, s79, 0
	s_mov_b32 m0, s35
	v_lshl_add_u64 v[186:187], s[66:67], 0, v[192:193]
	ds_read_b128 v[154:157], v139 offset:32768
	ds_read_b128 v[158:161], v139 offset:33792
	ds_read_b128 v[162:165], v139 offset:34816
	ds_read_b128 v[166:169], v139 offset:35840
	ds_read_b128 v[170:173], v139 offset:36864
	ds_read_b128 v[174:177], v139 offset:37888
	ds_read_b128 v[178:181], v139 offset:38912
	ds_read_b128 v[182:185], v139 offset:39936
	global_load_lds_dwordx4 v[186:187], off
	v_lshl_add_u64 v[186:187], s[66:67], 0, v[128:129]
	s_mov_b32 m0, s4
	s_nop 0
	global_load_lds_dwordx4 v[186:187], off
	s_waitcnt lgkmcnt(8)
	s_barrier
	s_waitcnt lgkmcnt(0)
	s_waitcnt lgkmcnt(0)
	v_mfma_f32_16x16x32_bf16 v[124:127], v[134:137], v[154:157], v[124:127]
	v_mfma_f32_16x16x32_bf16 v[120:123], v[146:149], v[154:157], v[120:123]
	v_mfma_f32_16x16x32_bf16 v[108:111], v[134:137], v[162:165], v[108:111]
	v_mfma_f32_16x16x32_bf16 v[104:107], v[146:149], v[162:165], v[104:107]
	v_mfma_f32_16x16x32_bf16 v[92:95], v[134:137], v[170:173], v[92:95]
	v_mfma_f32_16x16x32_bf16 v[88:91], v[146:149], v[170:173], v[88:91]
	v_mfma_f32_16x16x32_bf16 v[76:79], v[134:137], v[178:181], v[76:79]
	v_mfma_f32_16x16x32_bf16 v[72:75], v[146:149], v[178:181], v[72:75]
	v_mfma_f32_16x16x32_bf16 v[124:127], v[142:145], v[158:161], v[124:127]
	v_mfma_f32_16x16x32_bf16 v[120:123], v[150:153], v[158:161], v[120:123]
	v_mfma_f32_16x16x32_bf16 v[108:111], v[142:145], v[166:169], v[108:111]
	v_mfma_f32_16x16x32_bf16 v[104:107], v[150:153], v[166:169], v[104:107]
	v_mfma_f32_16x16x32_bf16 v[92:95], v[142:145], v[174:177], v[92:95]
	v_mfma_f32_16x16x32_bf16 v[88:91], v[150:153], v[174:177], v[88:91]
	v_mfma_f32_16x16x32_bf16 v[76:79], v[142:145], v[182:185], v[76:79]
	v_mfma_f32_16x16x32_bf16 v[72:75], v[150:153], v[182:185], v[72:75]
	s_barrier
	s_mov_b32 m0, s5
	v_or_b32_e32 v186, 0x1c000, v140
	v_add_u32_e32 v194, 0x1c400, v140
	v_add_u32_e32 v198, 0x1c800, v140
	v_add_u32_e32 v202, 0x1cc00, v140
	v_lshl_add_u64 v[190:191], v[190:191], 0, s[90:91]
	ds_read_b128 v[186:189], v186
	ds_read_b128 v[194:197], v194
	ds_read_b128 v[198:201], v198
	ds_read_b128 v[202:205], v202
	global_load_lds_dwordx4 v[190:191], off
	v_lshl_add_u64 v[190:191], v[206:207], 0, s[90:91]
	s_mov_b32 m0, s82
	s_nop 0
	global_load_lds_dwordx4 v[190:191], off
	s_barrier
	s_waitcnt lgkmcnt(0)
	s_waitcnt lgkmcnt(0)
	v_mfma_f32_16x16x32_bf16 v[116:119], v[186:189], v[154:157], v[116:119]
	v_mfma_f32_16x16x32_bf16 v[112:115], v[198:201], v[154:157], v[112:115]
	v_mfma_f32_16x16x32_bf16 v[100:103], v[186:189], v[162:165], v[100:103]
	v_mfma_f32_16x16x32_bf16 v[96:99], v[198:201], v[162:165], v[96:99]
	v_mfma_f32_16x16x32_bf16 v[84:87], v[186:189], v[170:173], v[84:87]
	v_mfma_f32_16x16x32_bf16 v[80:83], v[198:201], v[170:173], v[80:83]
	v_mfma_f32_16x16x32_bf16 v[68:71], v[186:189], v[178:181], v[68:71]
	v_mfma_f32_16x16x32_bf16 v[64:67], v[198:201], v[178:181], v[64:67]
	v_mfma_f32_16x16x32_bf16 v[116:119], v[194:197], v[158:161], v[116:119]
	v_mfma_f32_16x16x32_bf16 v[112:115], v[202:205], v[158:161], v[112:115]
	v_mfma_f32_16x16x32_bf16 v[100:103], v[194:197], v[166:169], v[100:103]
	v_mfma_f32_16x16x32_bf16 v[96:99], v[202:205], v[166:169], v[96:99]
	v_mfma_f32_16x16x32_bf16 v[84:87], v[194:197], v[174:177], v[84:87]
	v_mfma_f32_16x16x32_bf16 v[80:83], v[202:205], v[174:177], v[80:83]
	v_mfma_f32_16x16x32_bf16 v[68:71], v[194:197], v[182:185], v[68:71]
	v_mfma_f32_16x16x32_bf16 v[64:67], v[202:205], v[182:185], v[64:67]
	s_mov_b32 m0, s83
	v_lshl_add_u64 v[190:191], v[208:209], 0, s[90:91]
	s_barrier
	ds_read_b128 v[154:157], v139 offset:49152
	ds_read_b128 v[158:161], v139 offset:50176
	ds_read_b128 v[162:165], v139 offset:51200
	ds_read_b128 v[166:169], v139 offset:52224
	ds_read_b128 v[170:173], v139 offset:53248
	ds_read_b128 v[174:177], v139 offset:54272
	ds_read_b128 v[178:181], v139 offset:55296
	ds_read_b128 v[182:185], v139 offset:56320
	global_load_lds_dwordx4 v[190:191], off
	v_lshl_add_u64 v[190:191], v[210:211], 0, s[90:91]
	s_mov_b32 m0, s84
	s_nop 0
	global_load_lds_dwordx4 v[190:191], off
	s_barrier
;   __device__ __forceinline__ bf16_t* XB() const { return (bf16_t*)(ws + 328 * MB); }
; #define G_STAGE(bufoff, gbase) do { _Pragma("unroll") for (int _i = 0; _i < 2; ++_i) \
;     __builtin_amdgcn_global_load_lds((const unsigned*)((const char*)(gbase) + voffA[_i]), (LAS unsigned*)(lds + (bufoff) + ldsw + _i * 8192), 16, 0, 0); } while (0)
; #define G_MMA(ai, bj, At, Bt) do { __builtin_amdgcn_s_setprio(1); _Pragma("unroll") for (int m = 0; m < 4; ++m) _Pragma("unroll") for (int n = 0; n < 2; ++n) _Pragma("unroll") for (int k = 0; k < 2; ++k) \
;     acc[ai][bj][m][n] = __builtin_amdgcn_mfma_f32_16x16x32_bf16(Bt[n][k], At[m][k], acc[ai][bj][m][n], 0, 0, 0); __builtin_amdgcn_s_setprio(0); } while (0)
; #define G_WAIT_V(n) asm volatile("s_waitcnt vmcnt(" #n ")" ::: "memory")
; #define G_WAIT_L(n) asm volatile("s_waitcnt lgkmcnt(" #n ")" ::: "memory")
; #define G_BAR __builtin_amdgcn_s_barrier()
; #define G_SCHED __builtin_amdgcn_sched_barrier(0)
; template <int MODE>
; __device__ __forceinline__ void gemm_epilogue(const Params& p, int layer, const f32x4 (&acc)[2][2][4][2], int pm, int pn, int wr, int wc, int fr, int fq) {
;     ...
;       } else if (MODE == 1) {
; #pragma unroll
;         for (int bj = 0; bj < 2; ++bj) { const int col = pn * 256 + bj * 128 + wc * 32 + 8 * fq;
;           bf16_t* xq = p.XB() + (size_t)row * DM + col; const u32x4 r = *(const u32x4*)xq; const f32x4 a0 = acc[ai][bj][m][0], a1 = acc[ai][bj][m][1];
; template <int MODE>
; __device__ __forceinline__ void gemm_phase(const Params& p, int layer, char* lds_generic) {
;     ...
;       G_BAR; G_WAIT_L(0); G_MMA(1, 0, At, B0); G_BAR; G_SCHED;
;       G_STAGE(G_SB(1, 1), b3 + hstep);
;       G_WAIT_V(6); G_BAR; G_MMA(1, 1, At, B1); G_BAR;
;     }
	s_waitcnt lgkmcnt(0)
	s_waitcnt lgkmcnt(0)
	v_mfma_f32_16x16x32_bf16 v[60:63], v[134:137], v[154:157], v[60:63]
	v_mfma_f32_16x16x32_bf16 v[56:59], v[146:149], v[154:157], v[56:59]
	v_mfma_f32_16x16x32_bf16 v[44:47], v[134:137], v[162:165], v[44:47]
	v_mfma_f32_16x16x32_bf16 v[40:43], v[146:149], v[162:165], v[40:43]
	v_mfma_f32_16x16x32_bf16 v[28:31], v[134:137], v[170:173], v[28:31]
	v_mfma_f32_16x16x32_bf16 v[24:27], v[146:149], v[170:173], v[24:27]
	v_mfma_f32_16x16x32_bf16 v[12:15], v[134:137], v[178:181], v[12:15]
	v_mfma_f32_16x16x32_bf16 v[8:11], v[146:149], v[178:181], v[8:11]
	v_mfma_f32_16x16x32_bf16 v[60:63], v[142:145], v[158:161], v[60:63]
	v_mfma_f32_16x16x32_bf16 v[56:59], v[150:153], v[158:161], v[56:59]
	v_mfma_f32_16x16x32_bf16 v[44:47], v[142:145], v[166:169], v[44:47]
	v_mfma_f32_16x16x32_bf16 v[40:43], v[150:153], v[166:169], v[40:43]
	v_mfma_f32_16x16x32_bf16 v[28:31], v[142:145], v[174:177], v[28:31]
	v_mfma_f32_16x16x32_bf16 v[24:27], v[150:153], v[174:177], v[24:27]
	v_mfma_f32_16x16x32_bf16 v[12:15], v[142:145], v[182:185], v[12:15]
	v_mfma_f32_16x16x32_bf16 v[8:11], v[150:153], v[182:185], v[8:11]
	s_barrier
	s_add_u32 s66, s76, 0x80080
	s_addc_u32 s67, s77, 0
	s_mov_b32 m0, s85
	v_lshl_add_u64 v[134:135], s[66:67], 0, v[192:193]
	global_load_lds_dwordx4 v[134:135], off
	v_lshl_add_u64 v[134:135], s[66:67], 0, v[128:129]
	s_mov_b32 m0, s80
	s_nop 0
	global_load_lds_dwordx4 v[134:135], off
	s_waitcnt vmcnt(6)
	s_barrier
	v_mfma_f32_16x16x32_bf16 v[52:55], v[186:189], v[154:157], v[52:55]
	v_mfma_f32_16x16x32_bf16 v[48:51], v[198:201], v[154:157], v[48:51]
	v_mfma_f32_16x16x32_bf16 v[36:39], v[186:189], v[162:165], v[36:39]
	v_mfma_f32_16x16x32_bf16 v[32:35], v[198:201], v[162:165], v[32:35]
	v_mfma_f32_16x16x32_bf16 v[20:23], v[186:189], v[170:173], v[20:23]
	v_mfma_f32_16x16x32_bf16 v[16:19], v[198:201], v[170:173], v[16:19]
	v_mfma_f32_16x16x32_bf16 v[4:7], v[186:189], v[178:181], v[4:7]
	v_mfma_f32_16x16x32_bf16 v[0:3], v[198:201], v[178:181], v[0:3]
	v_mfma_f32_16x16x32_bf16 v[52:55], v[194:197], v[158:161], v[52:55]
	v_mfma_f32_16x16x32_bf16 v[48:51], v[202:205], v[158:161], v[48:51]
	v_mfma_f32_16x16x32_bf16 v[36:39], v[194:197], v[166:169], v[36:39]
	v_mfma_f32_16x16x32_bf16 v[32:35], v[202:205], v[166:169], v[32:35]
	v_mfma_f32_16x16x32_bf16 v[20:23], v[194:197], v[174:177], v[20:23]
	v_mfma_f32_16x16x32_bf16 v[16:19], v[202:205], v[174:177], v[16:19]
	v_mfma_f32_16x16x32_bf16 v[4:7], v[194:197], v[182:185], v[4:7]
	v_mfma_f32_16x16x32_bf16 v[0:3], v[202:205], v[182:185], v[0:3]
	s_add_i32 s9, s9, 2
	s_add_u32 vcc_lo, vcc_lo, 0x100
	s_addc_u32 vcc_hi, vcc_hi, 0
	s_add_u32 s89, s89, 0x100
	s_addc_u32 s60, s60, 0
	s_cmp_gt_u32 s9, 29
	s_barrier
	s_cbranch_scc0 .LBB0_103
	v_lshl_add_u32 v134, s62, 8, v138
	v_lshl_or_b32 v136, s63, 8, v141
	v_ashrrev_i32_e32 v135, 31, v134
	v_lshlrev_b64 v[142:143], 12, v[134:135]
	v_ashrrev_i32_e32 v137, 31, v136
	v_lshl_add_u64 v[142:143], s[6:7], 0, v[142:143]
	v_lshlrev_b64 v[136:137], 1, v[136:137]
	v_lshl_add_u64 v[146:147], v[142:143], 0, v[136:137]
	global_load_dwordx4 v[148:151], v[146:147], off
	global_load_dwordx4 v[152:155], v[146:147], off offset:256
	s_mov_b64 s[100:101], 0x10000
	v_lshl_add_u64 v[210:211], v[146:147], 0, s[100:101]
	global_load_dwordx4 v[156:159], v[210:211], off
	global_load_dwordx4 v[160:163], v[210:211], off offset:256
	s_mov_b64 s[100:101], 0x20000
	v_lshl_add_u64 v[210:211], v[146:147], 0, s[100:101]
	global_load_dwordx4 v[164:167], v[210:211], off
	global_load_dwordx4 v[168:171], v[210:211], off offset:256
	s_mov_b64 s[100:101], 0x30000
	v_lshl_add_u64 v[210:211], v[146:147], 0, s[100:101]
	global_load_dwordx4 v[172:175], v[210:211], off
	global_load_dwordx4 v[176:179], v[210:211], off offset:256
	s_mov_b64 s[100:101], 0x80000
	v_lshl_add_u64 v[210:211], v[146:147], 0, s[100:101]
	global_load_dwordx4 v[180:183], v[210:211], off
	global_load_dwordx4 v[184:187], v[210:211], off offset:256
	s_mov_b64 s[100:101], 0x90000
	v_lshl_add_u64 v[210:211], v[146:147], 0, s[100:101]
	global_load_dwordx4 v[194:197], v[210:211], off
	global_load_dwordx4 v[198:201], v[210:211], off offset:256
	s_mov_b64 s[100:101], 0xa0000
	v_lshl_add_u64 v[210:211], v[146:147], 0, s[100:101]
	global_load_dwordx4 v[202:205], v[210:211], off
	global_load_dwordx4 v[206:209], v[210:211], off offset:256
	s_mov_b64 s[100:101], 0xb0000
	v_lshl_add_u64 v[210:211], v[146:147], 0, s[100:101]
	global_load_dwordx4 v[216:219], v[210:211], off
	global_load_dwordx4 v[222:225], v[210:211], off offset:256
	s_and_b64 vcc, exec, s[72:73]
	s_mov_b32 s62, s68
	s_mov_b32 s63, s70
	s_mov_b64 s[78:79], s[74:75]
	s_mov_b64 s[76:77], s[86:87]
	s_waitcnt vmcnt(0)
;   __device__ __forceinline__ bf16_t* XB() const { return (bf16_t*)(ws + 328 * MB); }
; __device__ __forceinline__ float bflo(unsigned w) { return __uint_as_float(w << 16); }
; __device__ __forceinline__ float bfhi(unsigned w) { return __uint_as_float(w & 0xffff0000u); }
; template <int MODE>
; __device__ __forceinline__ void gemm_epilogue(const Params& p, int layer, const f32x4 (&acc)[2][2][4][2], int pm, int pn, int wr, int wc, int fr, int fq) {
;     ...
;       } else if (MODE == 1) {
; #pragma unroll
;         for (int bj = 0; bj < 2; ++bj) { const int col = pn * 256 + bj * 128 + wc * 32 + 8 * fq;
;           bf16_t* xq = p.XB() + (size_t)row * DM + col; const u32x4 r = *(const u32x4*)xq; const f32x4 a0 = acc[ai][bj][m][0], a1 = acc[ai][bj][m][1];
;           const u32x4 w = {cvtpk(a0[0] + bflo(r[0]), a0[1] + bfhi(r[0])), cvtpk(a0[2] + bflo(r[1]), a0[3] + bfhi(r[1])), cvtpk(a1[0] + bflo(r[2]), a1[1] + bfhi(r[2])), cvtpk(a1[2] + bflo(r[3]), a1[3] + bfhi(r[3]))};
;           *(u32x4*)xq = w; }
	v_mov_b64_e32 v[142:143], v[148:149]
	v_mov_b64_e32 v[144:145], v[150:151]
	v_lshlrev_b32_e32 v135, 16, v142
	v_add_f32_e32 v124, v124, v135
	v_and_b32_e32 v135, 0xffff0000, v142
	v_add_f32_e32 v125, v125, v135
	v_cvt_pk_bf16_f32 v124, v124, v125
	v_lshlrev_b32_e32 v125, 16, v143
	v_add_f32_e32 v125, v126, v125
	v_and_b32_e32 v126, 0xffff0000, v143
	v_add_f32_e32 v126, v127, v126
	v_cvt_pk_bf16_f32 v125, v125, v126
	v_lshlrev_b32_e32 v126, 16, v144
	v_add_f32_e32 v120, v120, v126
	v_and_b32_e32 v126, 0xffff0000, v144
	v_add_f32_e32 v121, v121, v126
	v_cvt_pk_bf16_f32 v126, v120, v121
	v_lshlrev_b32_e32 v120, 16, v145
	v_and_b32_e32 v121, 0xffff0000, v145
	v_add_f32_e32 v120, v122, v120
	v_add_f32_e32 v121, v123, v121
	v_cvt_pk_bf16_f32 v127, v120, v121
	v_mov_b64_e32 v[120:121], v[152:153]
	v_mov_b64_e32 v[122:123], v[154:155]
	s_nop 0
	global_store_dwordx4 v[146:147], v[124:127], off
	s_nop 0
	v_lshlrev_b32_e32 v124, 16, v120
	v_and_b32_e32 v120, 0xffff0000, v120
	v_add_f32_e32 v116, v116, v124
	v_add_f32_e32 v117, v117, v120
	v_cvt_pk_bf16_f32 v116, v116, v117
	v_lshlrev_b32_e32 v117, 16, v121
	v_add_f32_e32 v117, v118, v117
	v_and_b32_e32 v118, 0xffff0000, v121
	v_add_f32_e32 v118, v119, v118
	v_cvt_pk_bf16_f32 v117, v117, v118
	v_lshlrev_b32_e32 v118, 16, v122
	v_add_f32_e32 v112, v112, v118
	v_and_b32_e32 v118, 0xffff0000, v122
	v_add_f32_e32 v113, v113, v118
	v_cvt_pk_bf16_f32 v118, v112, v113
	v_lshlrev_b32_e32 v112, 16, v123
	v_add_f32_e32 v112, v114, v112
	v_and_b32_e32 v113, 0xffff0000, v123
	v_add_f32_e32 v113, v115, v113
	v_cvt_pk_bf16_f32 v119, v112, v113
	v_or_b32_e32 v112, 16, v134
	v_ashrrev_i32_e32 v113, 31, v112
	v_lshlrev_b64 v[112:113], 12, v[112:113]
	v_lshl_add_u64 v[112:113], s[6:7], 0, v[112:113]
	global_store_dwordx4 v[146:147], v[116:119], off offset:256
	s_nop 1
	v_lshl_add_u64 v[116:117], v[112:113], 0, v[136:137]
	v_mov_b64_e32 v[112:113], v[156:157]
	v_mov_b64_e32 v[114:115], v[158:159]
	v_lshlrev_b32_e32 v118, 16, v112
	v_and_b32_e32 v112, 0xffff0000, v112
	v_add_f32_e32 v108, v108, v118
	v_add_f32_e32 v109, v109, v112
	v_cvt_pk_bf16_f32 v108, v108, v109
	v_lshlrev_b32_e32 v109, 16, v113
	v_add_f32_e32 v109, v110, v109
	v_and_b32_e32 v110, 0xffff0000, v113
	v_add_f32_e32 v110, v111, v110
	v_cvt_pk_bf16_f32 v109, v109, v110
	v_lshlrev_b32_e32 v110, 16, v114
	v_add_f32_e32 v104, v104, v110
	v_and_b32_e32 v110, 0xffff0000, v114
	v_add_f32_e32 v105, v105, v110
	v_cvt_pk_bf16_f32 v110, v104, v105
	v_lshlrev_b32_e32 v104, 16, v115
	v_and_b32_e32 v105, 0xffff0000, v115
	v_add_f32_e32 v104, v106, v104
	v_add_f32_e32 v105, v107, v105
	v_cvt_pk_bf16_f32 v111, v104, v105
	v_mov_b64_e32 v[104:105], v[160:161]
	v_mov_b64_e32 v[106:107], v[162:163]
	s_nop 0
	global_store_dwordx4 v[116:117], v[108:111], off
	s_nop 0
	v_lshlrev_b32_e32 v108, 16, v104
	v_and_b32_e32 v104, 0xffff0000, v104
	v_add_f32_e32 v100, v100, v108
	v_add_f32_e32 v101, v101, v104
	v_cvt_pk_bf16_f32 v100, v100, v101
	v_lshlrev_b32_e32 v101, 16, v105
	v_add_f32_e32 v101, v102, v101
	v_and_b32_e32 v102, 0xffff0000, v105
	v_add_f32_e32 v102, v103, v102
	v_cvt_pk_bf16_f32 v101, v101, v102
	v_lshlrev_b32_e32 v102, 16, v106
	v_add_f32_e32 v96, v96, v102
	v_and_b32_e32 v102, 0xffff0000, v106
	v_add_f32_e32 v97, v97, v102
	v_cvt_pk_bf16_f32 v102, v96, v97
	v_lshlrev_b32_e32 v96, 16, v107
	v_add_f32_e32 v96, v98, v96
	v_and_b32_e32 v97, 0xffff0000, v107
	v_add_f32_e32 v97, v99, v97
	v_cvt_pk_bf16_f32 v103, v96, v97
	v_or_b32_e32 v96, 32, v134
	v_ashrrev_i32_e32 v97, 31, v96
	v_lshlrev_b64 v[96:97], 12, v[96:97]
	v_lshl_add_u64 v[96:97], s[6:7], 0, v[96:97]
	global_store_dwordx4 v[116:117], v[100:103], off offset:256
	s_nop 1
	v_lshl_add_u64 v[100:101], v[96:97], 0, v[136:137]
	v_mov_b64_e32 v[96:97], v[164:165]
	v_mov_b64_e32 v[98:99], v[166:167]
	v_lshlrev_b32_e32 v102, 16, v96
	v_and_b32_e32 v96, 0xffff0000, v96
	v_add_f32_e32 v92, v92, v102
	v_add_f32_e32 v93, v93, v96
	v_cvt_pk_bf16_f32 v92, v92, v93
	v_lshlrev_b32_e32 v93, 16, v97
	v_add_f32_e32 v93, v94, v93
	v_and_b32_e32 v94, 0xffff0000, v97
	v_add_f32_e32 v94, v95, v94
	v_cvt_pk_bf16_f32 v93, v93, v94
	v_lshlrev_b32_e32 v94, 16, v98
	v_add_f32_e32 v88, v88, v94
	v_and_b32_e32 v94, 0xffff0000, v98
	v_add_f32_e32 v89, v89, v94
	v_cvt_pk_bf16_f32 v94, v88, v89
	v_lshlrev_b32_e32 v88, 16, v99
	v_and_b32_e32 v89, 0xffff0000, v99
	v_add_f32_e32 v88, v90, v88
	v_add_f32_e32 v89, v91, v89
	v_cvt_pk_bf16_f32 v95, v88, v89
	v_mov_b64_e32 v[88:89], v[168:169]
	v_mov_b64_e32 v[90:91], v[170:171]
	s_nop 0
	global_store_dwordx4 v[100:101], v[92:95], off
	s_nop 0
	v_lshlrev_b32_e32 v92, 16, v88
	v_and_b32_e32 v88, 0xffff0000, v88
	v_add_f32_e32 v84, v84, v92
	v_add_f32_e32 v85, v85, v88
	v_cvt_pk_bf16_f32 v84, v84, v85
	v_lshlrev_b32_e32 v85, 16, v89
	v_add_f32_e32 v85, v86, v85
	v_and_b32_e32 v86, 0xffff0000, v89
	v_add_f32_e32 v86, v87, v86
	v_cvt_pk_bf16_f32 v85, v85, v86
	v_lshlrev_b32_e32 v86, 16, v90
	v_add_f32_e32 v80, v80, v86
	v_and_b32_e32 v86, 0xffff0000, v90
	v_add_f32_e32 v81, v81, v86
	v_cvt_pk_bf16_f32 v86, v80, v81
	v_lshlrev_b32_e32 v80, 16, v91
	v_add_f32_e32 v80, v82, v80
	v_and_b32_e32 v81, 0xffff0000, v91
	v_add_f32_e32 v81, v83, v81
	v_cvt_pk_bf16_f32 v87, v80, v81
	v_or_b32_e32 v80, 48, v134
	v_ashrrev_i32_e32 v81, 31, v80
	v_lshlrev_b64 v[80:81], 12, v[80:81]
	v_lshl_add_u64 v[80:81], s[6:7], 0, v[80:81]
	global_store_dwordx4 v[100:101], v[84:87], off offset:256
	s_nop 1
	v_lshl_add_u64 v[84:85], v[80:81], 0, v[136:137]
	v_mov_b64_e32 v[80:81], v[172:173]
	v_mov_b64_e32 v[82:83], v[174:175]
	v_lshlrev_b32_e32 v86, 16, v80
	v_and_b32_e32 v80, 0xffff0000, v80
	v_add_f32_e32 v76, v76, v86
;   __device__ __forceinline__ bf16_t* XB() const { return (bf16_t*)(ws + 328 * MB); }
; __device__ __forceinline__ float bflo(unsigned w) { return __uint_as_float(w << 16); }
; __device__ __forceinline__ float bfhi(unsigned w) { return __uint_as_float(w & 0xffff0000u); }
; template <int MODE>
; __device__ __forceinline__ void gemm_epilogue(const Params& p, int layer, const f32x4 (&acc)[2][2][4][2], int pm, int pn, int wr, int wc, int fr, int fq) {
;     ...
;       } else if (MODE == 1) {
; #pragma unroll
;         for (int bj = 0; bj < 2; ++bj) { const int col = pn * 256 + bj * 128 + wc * 32 + 8 * fq;
;           bf16_t* xq = p.XB() + (size_t)row * DM + col; const u32x4 r = *(const u32x4*)xq; const f32x4 a0 = acc[ai][bj][m][0], a1 = acc[ai][bj][m][1];
;           const u32x4 w = {cvtpk(a0[0] + bflo(r[0]), a0[1] + bfhi(r[0])), cvtpk(a0[2] + bflo(r[1]), a0[3] + bfhi(r[1])), cvtpk(a1[0] + bflo(r[2]), a1[1] + bfhi(r[2])), cvtpk(a1[2] + bflo(r[3]), a1[3] + bfhi(r[3]))};
;           *(u32x4*)xq = w; }
	v_add_f32_e32 v77, v77, v80
	v_cvt_pk_bf16_f32 v76, v76, v77
	v_lshlrev_b32_e32 v77, 16, v81
	v_add_f32_e32 v77, v78, v77
	v_and_b32_e32 v78, 0xffff0000, v81
	v_add_f32_e32 v78, v79, v78
	v_cvt_pk_bf16_f32 v77, v77, v78
	v_lshlrev_b32_e32 v78, 16, v82
	v_add_f32_e32 v72, v72, v78
	v_and_b32_e32 v78, 0xffff0000, v82
	v_add_f32_e32 v73, v73, v78
	v_cvt_pk_bf16_f32 v78, v72, v73
	v_lshlrev_b32_e32 v72, 16, v83
	v_and_b32_e32 v73, 0xffff0000, v83
	v_add_f32_e32 v72, v74, v72
	v_add_f32_e32 v73, v75, v73
	v_cvt_pk_bf16_f32 v79, v72, v73
	v_mov_b64_e32 v[72:73], v[176:177]
	v_mov_b64_e32 v[74:75], v[178:179]
	s_nop 0
	global_store_dwordx4 v[84:85], v[76:79], off
	s_nop 0
	v_lshlrev_b32_e32 v76, 16, v72
	v_and_b32_e32 v72, 0xffff0000, v72
	v_add_f32_e32 v68, v68, v76
	v_add_f32_e32 v69, v69, v72
	v_cvt_pk_bf16_f32 v68, v68, v69
	v_lshlrev_b32_e32 v69, 16, v73
	v_add_f32_e32 v69, v70, v69
	v_and_b32_e32 v70, 0xffff0000, v73
	v_add_f32_e32 v70, v71, v70
	v_cvt_pk_bf16_f32 v69, v69, v70
	v_lshlrev_b32_e32 v70, 16, v74
	v_add_f32_e32 v64, v64, v70
	v_and_b32_e32 v70, 0xffff0000, v74
	v_add_f32_e32 v65, v65, v70
	v_cvt_pk_bf16_f32 v70, v64, v65
	v_lshlrev_b32_e32 v64, 16, v75
	v_add_f32_e32 v64, v66, v64
	v_and_b32_e32 v65, 0xffff0000, v75
	v_add_f32_e32 v65, v67, v65
	v_cvt_pk_bf16_f32 v71, v64, v65
	v_add_u32_e32 v64, 0x80, v134
	v_ashrrev_i32_e32 v65, 31, v64
	v_lshlrev_b64 v[64:65], 12, v[64:65]
	v_lshl_add_u64 v[64:65], s[6:7], 0, v[64:65]
	global_store_dwordx4 v[84:85], v[68:71], off offset:256
	s_nop 1
	v_lshl_add_u64 v[68:69], v[64:65], 0, v[136:137]
	v_mov_b64_e32 v[64:65], v[180:181]
	v_mov_b64_e32 v[66:67], v[182:183]
	v_lshlrev_b32_e32 v70, 16, v64
	v_and_b32_e32 v64, 0xffff0000, v64
	v_add_f32_e32 v60, v60, v70
	v_add_f32_e32 v61, v61, v64
	v_cvt_pk_bf16_f32 v60, v60, v61
	v_lshlrev_b32_e32 v61, 16, v65
	v_add_f32_e32 v61, v62, v61
	v_and_b32_e32 v62, 0xffff0000, v65
	v_add_f32_e32 v62, v63, v62
	v_cvt_pk_bf16_f32 v61, v61, v62
	v_lshlrev_b32_e32 v62, 16, v66
	v_add_f32_e32 v56, v56, v62
	v_and_b32_e32 v62, 0xffff0000, v66
	v_add_f32_e32 v57, v57, v62
	v_cvt_pk_bf16_f32 v62, v56, v57
	v_lshlrev_b32_e32 v56, 16, v67
	v_and_b32_e32 v57, 0xffff0000, v67
	v_add_f32_e32 v56, v58, v56
	v_add_f32_e32 v57, v59, v57
	v_cvt_pk_bf16_f32 v63, v56, v57
	v_mov_b64_e32 v[56:57], v[184:185]
	v_mov_b64_e32 v[58:59], v[186:187]
	s_nop 0
	global_store_dwordx4 v[68:69], v[60:63], off
	s_nop 0
	v_lshlrev_b32_e32 v60, 16, v56
	v_and_b32_e32 v56, 0xffff0000, v56
	v_add_f32_e32 v52, v52, v60
	v_add_f32_e32 v53, v53, v56
	v_cvt_pk_bf16_f32 v52, v52, v53
	v_lshlrev_b32_e32 v53, 16, v57
	v_add_f32_e32 v53, v54, v53
	v_and_b32_e32 v54, 0xffff0000, v57
	v_add_f32_e32 v54, v55, v54
	v_cvt_pk_bf16_f32 v53, v53, v54
	v_lshlrev_b32_e32 v54, 16, v58
	v_add_f32_e32 v48, v48, v54
	v_and_b32_e32 v54, 0xffff0000, v58
	v_add_f32_e32 v49, v49, v54
	v_cvt_pk_bf16_f32 v54, v48, v49
	v_lshlrev_b32_e32 v48, 16, v59
	v_add_f32_e32 v48, v50, v48
	v_and_b32_e32 v49, 0xffff0000, v59
	v_add_f32_e32 v49, v51, v49
	v_cvt_pk_bf16_f32 v55, v48, v49
	v_add_u32_e32 v48, 0x90, v134
	v_ashrrev_i32_e32 v49, 31, v48
	v_lshlrev_b64 v[48:49], 12, v[48:49]
	v_lshl_add_u64 v[48:49], s[6:7], 0, v[48:49]
	global_store_dwordx4 v[68:69], v[52:55], off offset:256
	s_nop 1
	v_lshl_add_u64 v[52:53], v[48:49], 0, v[136:137]
	v_mov_b64_e32 v[48:49], v[194:195]
	v_mov_b64_e32 v[50:51], v[196:197]
	v_lshlrev_b32_e32 v54, 16, v48
	v_and_b32_e32 v48, 0xffff0000, v48
	v_add_f32_e32 v44, v44, v54
	v_add_f32_e32 v45, v45, v48
	v_cvt_pk_bf16_f32 v44, v44, v45
	v_lshlrev_b32_e32 v45, 16, v49
	v_add_f32_e32 v45, v46, v45
	v_and_b32_e32 v46, 0xffff0000, v49
	v_add_f32_e32 v46, v47, v46
	v_cvt_pk_bf16_f32 v45, v45, v46
	v_lshlrev_b32_e32 v46, 16, v50
	v_add_f32_e32 v40, v40, v46
	v_and_b32_e32 v46, 0xffff0000, v50
	v_add_f32_e32 v41, v41, v46
	v_cvt_pk_bf16_f32 v46, v40, v41
	v_lshlrev_b32_e32 v40, 16, v51
	v_and_b32_e32 v41, 0xffff0000, v51
	v_add_f32_e32 v40, v42, v40
	v_add_f32_e32 v41, v43, v41
	v_cvt_pk_bf16_f32 v47, v40, v41
	v_mov_b64_e32 v[40:41], v[198:199]
	v_mov_b64_e32 v[42:43], v[200:201]
	s_nop 0
	global_store_dwordx4 v[52:53], v[44:47], off
	s_nop 0
	v_lshlrev_b32_e32 v44, 16, v40
	v_and_b32_e32 v40, 0xffff0000, v40
	v_add_f32_e32 v36, v36, v44
;   __device__ __forceinline__ bf16_t* XB() const { return (bf16_t*)(ws + 328 * MB); }
; __device__ __forceinline__ float bflo(unsigned w) { return __uint_as_float(w << 16); }
; __device__ __forceinline__ float bfhi(unsigned w) { return __uint_as_float(w & 0xffff0000u); }
; template <int MODE>
; __device__ __forceinline__ void gemm_epilogue(const Params& p, int layer, const f32x4 (&acc)[2][2][4][2], int pm, int pn, int wr, int wc, int fr, int fq) {
;     ...
;       } else if (MODE == 1) {
; #pragma unroll
;         for (int bj = 0; bj < 2; ++bj) { const int col = pn * 256 + bj * 128 + wc * 32 + 8 * fq;
;           bf16_t* xq = p.XB() + (size_t)row * DM + col; const u32x4 r = *(const u32x4*)xq; const f32x4 a0 = acc[ai][bj][m][0], a1 = acc[ai][bj][m][1];
;           const u32x4 w = {cvtpk(a0[0] + bflo(r[0]), a0[1] + bfhi(r[0])), cvtpk(a0[2] + bflo(r[1]), a0[3] + bfhi(r[1])), cvtpk(a1[0] + bflo(r[2]), a1[1] + bfhi(r[2])), cvtpk(a1[2] + bflo(r[3]), a1[3] + bfhi(r[3]))};
;           *(u32x4*)xq = w; }
; template <int MODE>
; __device__ __forceinline__ void gemm_phase(const Params& p, int layer, char* lds_generic) {
;     ...
;     if (!has_next) break;
	v_add_f32_e32 v37, v37, v40
	v_cvt_pk_bf16_f32 v36, v36, v37
	v_lshlrev_b32_e32 v37, 16, v41
	v_add_f32_e32 v37, v38, v37
	v_and_b32_e32 v38, 0xffff0000, v41
	v_add_f32_e32 v38, v39, v38
	v_cvt_pk_bf16_f32 v37, v37, v38
	v_lshlrev_b32_e32 v38, 16, v42
	v_add_f32_e32 v32, v32, v38
	v_and_b32_e32 v38, 0xffff0000, v42
	v_add_f32_e32 v33, v33, v38
	v_cvt_pk_bf16_f32 v38, v32, v33
	v_lshlrev_b32_e32 v32, 16, v43
	v_add_f32_e32 v32, v34, v32
	v_and_b32_e32 v33, 0xffff0000, v43
	v_add_f32_e32 v33, v35, v33
	v_cvt_pk_bf16_f32 v39, v32, v33
	v_add_u32_e32 v32, 0xa0, v134
	v_ashrrev_i32_e32 v33, 31, v32
	v_lshlrev_b64 v[32:33], 12, v[32:33]
	v_lshl_add_u64 v[32:33], s[6:7], 0, v[32:33]
	global_store_dwordx4 v[52:53], v[36:39], off offset:256
	s_nop 1
	v_lshl_add_u64 v[36:37], v[32:33], 0, v[136:137]
	v_mov_b64_e32 v[32:33], v[202:203]
	v_mov_b64_e32 v[34:35], v[204:205]
	v_lshlrev_b32_e32 v38, 16, v32
	v_and_b32_e32 v32, 0xffff0000, v32
	v_add_f32_e32 v28, v28, v38
	v_add_f32_e32 v29, v29, v32
	v_cvt_pk_bf16_f32 v28, v28, v29
	v_lshlrev_b32_e32 v29, 16, v33
	v_add_f32_e32 v29, v30, v29
	v_and_b32_e32 v30, 0xffff0000, v33
	v_add_f32_e32 v30, v31, v30
	v_cvt_pk_bf16_f32 v29, v29, v30
	v_lshlrev_b32_e32 v30, 16, v34
	v_add_f32_e32 v24, v24, v30
	v_and_b32_e32 v30, 0xffff0000, v34
	v_add_f32_e32 v25, v25, v30
	v_cvt_pk_bf16_f32 v30, v24, v25
	v_lshlrev_b32_e32 v24, 16, v35
	v_and_b32_e32 v25, 0xffff0000, v35
	v_add_f32_e32 v24, v26, v24
	v_add_f32_e32 v25, v27, v25
	v_cvt_pk_bf16_f32 v31, v24, v25
	v_mov_b64_e32 v[24:25], v[206:207]
	v_mov_b64_e32 v[26:27], v[208:209]
	s_nop 0
	global_store_dwordx4 v[36:37], v[28:31], off
	s_nop 0
	v_lshlrev_b32_e32 v28, 16, v24
	v_and_b32_e32 v24, 0xffff0000, v24
	v_add_f32_e32 v20, v20, v28
	v_add_f32_e32 v21, v21, v24
	v_cvt_pk_bf16_f32 v20, v20, v21
	v_lshlrev_b32_e32 v21, 16, v25
	v_add_f32_e32 v21, v22, v21
	v_and_b32_e32 v22, 0xffff0000, v25
	v_add_f32_e32 v22, v23, v22
	v_cvt_pk_bf16_f32 v21, v21, v22
	v_lshlrev_b32_e32 v22, 16, v26
	v_add_f32_e32 v16, v16, v22
	v_and_b32_e32 v22, 0xffff0000, v26
	v_add_f32_e32 v17, v17, v22
	v_cvt_pk_bf16_f32 v22, v16, v17
	v_lshlrev_b32_e32 v16, 16, v27
	v_add_f32_e32 v16, v18, v16
	v_and_b32_e32 v17, 0xffff0000, v27
	v_add_f32_e32 v17, v19, v17
	v_cvt_pk_bf16_f32 v23, v16, v17
	v_add_u32_e32 v16, 0xb0, v134
	v_ashrrev_i32_e32 v17, 31, v16
	v_lshlrev_b64 v[16:17], 12, v[16:17]
	v_lshl_add_u64 v[16:17], s[6:7], 0, v[16:17]
	global_store_dwordx4 v[36:37], v[20:23], off offset:256
	s_nop 1
	v_lshl_add_u64 v[20:21], v[16:17], 0, v[136:137]
	v_mov_b64_e32 v[16:17], v[216:217]
	v_mov_b64_e32 v[18:19], v[218:219]
	v_lshlrev_b32_e32 v22, 16, v16
	v_and_b32_e32 v16, 0xffff0000, v16
	v_add_f32_e32 v12, v12, v22
	v_add_f32_e32 v13, v13, v16
	v_cvt_pk_bf16_f32 v12, v12, v13
	v_lshlrev_b32_e32 v13, 16, v17
	v_add_f32_e32 v13, v14, v13
	v_and_b32_e32 v14, 0xffff0000, v17
	v_add_f32_e32 v14, v15, v14
	v_cvt_pk_bf16_f32 v13, v13, v14
	v_lshlrev_b32_e32 v14, 16, v18
	v_add_f32_e32 v8, v8, v14
	v_and_b32_e32 v14, 0xffff0000, v18
	v_add_f32_e32 v9, v9, v14
	v_cvt_pk_bf16_f32 v14, v8, v9
	v_lshlrev_b32_e32 v8, 16, v19
	v_and_b32_e32 v9, 0xffff0000, v19
	v_add_f32_e32 v8, v10, v8
	v_add_f32_e32 v9, v11, v9
	v_cvt_pk_bf16_f32 v15, v8, v9
	v_mov_b64_e32 v[8:9], v[222:223]
	v_mov_b64_e32 v[10:11], v[224:225]
	s_nop 0
	global_store_dwordx4 v[20:21], v[12:15], off
	s_nop 0
	v_lshlrev_b32_e32 v12, 16, v8
	v_and_b32_e32 v8, 0xffff0000, v8
	v_add_f32_e32 v4, v4, v12
	v_add_f32_e32 v5, v5, v8
	v_cvt_pk_bf16_f32 v4, v4, v5
	v_lshlrev_b32_e32 v5, 16, v9
	v_add_f32_e32 v5, v6, v5
	v_and_b32_e32 v6, 0xffff0000, v9
	v_add_f32_e32 v6, v7, v6
	v_cvt_pk_bf16_f32 v5, v5, v6
	v_lshlrev_b32_e32 v6, 16, v10
	v_add_f32_e32 v0, v0, v6
	v_and_b32_e32 v6, 0xffff0000, v10
	v_add_f32_e32 v1, v1, v6
	v_cvt_pk_bf16_f32 v6, v0, v1
	v_lshlrev_b32_e32 v0, 16, v11
	v_and_b32_e32 v1, 0xffff0000, v11
	v_add_f32_e32 v0, v2, v0
	v_add_f32_e32 v1, v3, v1
	v_cvt_pk_bf16_f32 v7, v0, v1
	global_store_dwordx4 v[20:21], v[4:7], off offset:256
	s_cbranch_vccz .LBB0_100
	s_waitcnt vmcnt(0)
	v_readlane_b32 s82, v254, 24
	s_cmpk_gt_u32 s15, 0xff
	v_readlane_b32 s83, v254, 25
	s_mov_b64 s[84:85], s[16:17]
	v_readlane_b32 s63, v254, 27
	s_cbranch_scc1 .LBB0_107
	s_barrier

; #define G_STAGE(bufoff, gbase) do { _Pragma("unroll") for (int _i = 0; _i < 2; ++_i) \
;     __builtin_amdgcn_global_load_lds((const unsigned*)((const char*)(gbase) + voffA[_i]), (LAS unsigned*)(lds + (bufoff) + ldsw + _i * 8192), 16, 0, 0); } while (0)
; #define G_LDA(dst, b, h) do { _Pragma("unroll") for (int m = 0; m < 4; ++m) _Pragma("unroll") for (int k = 0; k < 2; ++k) dst[m][k] = *(const LAS bf16x8*)(lds + G_SA(b, h) + aoff + m * 2048 + k * 1024); } while (0)
; #define G_LDB(dst, b, h) do { _Pragma("unroll") for (int n = 0; n < 2; ++n) _Pragma("unroll") for (int k = 0; k < 2; ++k) dst[n][k] = *(const LAS bf16x8*)(lds + G_SB(b, h) + boff + n * 2048 + k * 1024); } while (0)
; #define G_MMA(ai, bj, At, Bt) do { __builtin_amdgcn_s_setprio(1); _Pragma("unroll") for (int m = 0; m < 4; ++m) _Pragma("unroll") for (int n = 0; n < 2; ++n) _Pragma("unroll") for (int k = 0; k < 2; ++k) \
;     acc[ai][bj][m][n] = __builtin_amdgcn_mfma_f32_16x16x32_bf16(Bt[n][k], At[m][k], acc[ai][bj][m][n], 0, 0, 0); __builtin_amdgcn_s_setprio(0); } while (0)
; #define G_WAIT_V(n) asm volatile("s_waitcnt vmcnt(" #n ")" ::: "memory")
; #define G_WAIT_L(n) asm volatile("s_waitcnt lgkmcnt(" #n ")" ::: "memory")
; #define G_BAR __builtin_amdgcn_s_barrier()
; #define G_SCHED __builtin_amdgcn_sched_barrier(0)
; template <int MODE>
; __device__ __forceinline__ void gemm_phase(const Params& p, int layer, char* lds_generic) {
;     ...
;     for (int t = 0; t < nt; t += 2) {
;       const bool last = (t == nt - 2);
;       const char* a1 = cA + (size_t)(t + 1) * kstep;
;       const char* a2 = last ? nA : cA + (size_t)(t + 2) * kstep; const char* b2 = last ? nB : cB + (size_t)(t + 2) * kstep;
;       const char* a3 = a2 + kstep; const char* b3 = b2 + kstep;
;       G_LDB(B0, 0, 0); G_SCHED; G_LDA(At, 0, 0); G_STAGE(G_SA(1, 1), a1 + hstep);
;       G_WAIT_L(8); G_BAR; G_WAIT_L(0); G_MMA(0, 0, At, B0); G_BAR; G_SCHED;
;       G_LDB(B1, 0, 1); G_STAGE(G_SB(0, 0), b2);
;       G_BAR; G_WAIT_L(0); G_MMA(0, 1, At, B1); G_BAR;
;       G_LDA(At, 0, 1); G_STAGE(G_SA(0, 0), a2);
;       G_BAR; G_WAIT_L(0); G_MMA(1, 0, At, B0); G_BAR; G_SCHED;
;       G_STAGE(G_SB(0, 1), b2 + hstep);
;       G_WAIT_V(6); G_BAR; G_MMA(1, 1, At, B1); G_BAR;
;       G_LDB(B0, 1, 0); G_SCHED; G_LDA(At, 1, 0); G_STAGE(G_SA(0, 1), a2 + hstep);
;       G_WAIT_L(8); G_BAR; G_WAIT_L(0); G_MMA(0, 0, At, B0); G_BAR; G_SCHED;
.LBB0_196:
	v_or_b32_e32 v128, 0x10000, v152
	v_add_u32_e32 v132, 0x10400, v152
	v_add_u32_e32 v136, 0x10800, v152
	ds_read_b128 v[128:131], v128
	ds_read_b128 v[132:135], v132
	v_add_u32_e32 v137, 0x10c00, v152
	ds_read_b128 v[146:149], v136
	ds_read_b128 v[154:157], v137
	s_add_u32 s6, s4, 0xfff80080
	s_addc_u32 s7, s5, -1
	s_cmp_eq_u32 s47, 28
	s_cselect_b32 s9, s2, s7
	s_cselect_b32 s8, s21, s6
	s_cselect_b32 s7, s23, s46
	s_cselect_b32 s6, s34, s35
	v_lshl_add_u64 v[136:137], s[4:5], 0, v[142:143]
	s_add_i32 m0, s68, 0xc000
	ds_read_b128 v[158:161], v151
	ds_read_b128 v[162:165], v151 offset:1024
	ds_read_b128 v[166:169], v151 offset:2048
	ds_read_b128 v[170:173], v151 offset:3072
	ds_read_b128 v[174:177], v151 offset:4096
	ds_read_b128 v[178:181], v151 offset:5120
	ds_read_b128 v[182:185], v151 offset:6144
	ds_read_b128 v[186:189], v151 offset:7168
	global_load_lds_dwordx4 v[136:137], off
	v_lshl_add_u64 v[136:137], s[4:5], 0, v[144:145]
	s_add_i32 m0, s68, 0xe000
	s_nop 0
	global_load_lds_dwordx4 v[136:137], off
	s_waitcnt lgkmcnt(8)
	s_barrier
	s_waitcnt lgkmcnt(0)
	s_waitcnt lgkmcnt(0)
	v_mfma_f32_16x16x32_bf16 v[124:127], v[128:131], v[158:161], v[124:127]
	v_mfma_f32_16x16x32_bf16 v[120:123], v[146:149], v[158:161], v[120:123]
	v_mfma_f32_16x16x32_bf16 v[108:111], v[128:131], v[166:169], v[108:111]
	v_mfma_f32_16x16x32_bf16 v[104:107], v[146:149], v[166:169], v[104:107]
	v_mfma_f32_16x16x32_bf16 v[92:95], v[128:131], v[174:177], v[92:95]
	v_mfma_f32_16x16x32_bf16 v[88:91], v[146:149], v[174:177], v[88:91]
	v_mfma_f32_16x16x32_bf16 v[76:79], v[128:131], v[182:185], v[76:79]
	v_mfma_f32_16x16x32_bf16 v[72:75], v[146:149], v[182:185], v[72:75]
	v_mfma_f32_16x16x32_bf16 v[124:127], v[132:135], v[162:165], v[124:127]
	v_mfma_f32_16x16x32_bf16 v[120:123], v[154:157], v[162:165], v[120:123]
	v_mfma_f32_16x16x32_bf16 v[108:111], v[132:135], v[170:173], v[108:111]
	v_mfma_f32_16x16x32_bf16 v[104:107], v[154:157], v[170:173], v[104:107]
	v_mfma_f32_16x16x32_bf16 v[92:95], v[132:135], v[178:181], v[92:95]
	v_mfma_f32_16x16x32_bf16 v[88:91], v[154:157], v[178:181], v[88:91]
	v_mfma_f32_16x16x32_bf16 v[76:79], v[132:135], v[186:189], v[76:79]
	v_mfma_f32_16x16x32_bf16 v[72:75], v[154:157], v[186:189], v[72:75]
	s_barrier
	v_or_b32_e32 v136, 0x14000, v152
	v_add_u32_e32 v137, 0x14400, v152
	ds_read_b128 v[194:197], v136
	ds_read_b128 v[198:201], v137
	v_add_u32_e32 v136, 0x14800, v152
	v_add_u32_e32 v137, 0x14c00, v152
	s_mov_b32 m0, s69
	ds_read_b128 v[202:205], v136
	ds_read_b128 v[228:231], v137
	v_lshl_add_u64 v[136:137], s[6:7], 0, v[140:141]
	global_load_lds_dwordx4 v[136:137], off
	v_lshl_add_u64 v[190:191], s[6:7], 0, v[138:139]
	s_mov_b32 m0, s70
	s_nop 0
	global_load_lds_dwordx4 v[190:191], off
	s_barrier
	s_waitcnt lgkmcnt(0)
	s_waitcnt lgkmcnt(0)
	v_mfma_f32_16x16x32_bf16 v[116:119], v[194:197], v[158:161], v[116:119]
	v_mfma_f32_16x16x32_bf16 v[112:115], v[202:205], v[158:161], v[112:115]
	v_mfma_f32_16x16x32_bf16 v[100:103], v[194:197], v[166:169], v[100:103]
	v_mfma_f32_16x16x32_bf16 v[96:99], v[202:205], v[166:169], v[96:99]
	v_mfma_f32_16x16x32_bf16 v[84:87], v[194:197], v[174:177], v[84:87]
	v_mfma_f32_16x16x32_bf16 v[80:83], v[202:205], v[174:177], v[80:83]
	v_mfma_f32_16x16x32_bf16 v[68:71], v[194:197], v[182:185], v[68:71]
	v_mfma_f32_16x16x32_bf16 v[64:67], v[202:205], v[182:185], v[64:67]
	v_mfma_f32_16x16x32_bf16 v[116:119], v[198:201], v[162:165], v[116:119]
	v_mfma_f32_16x16x32_bf16 v[112:115], v[228:231], v[162:165], v[112:115]
	v_mfma_f32_16x16x32_bf16 v[100:103], v[198:201], v[170:173], v[100:103]
	v_mfma_f32_16x16x32_bf16 v[96:99], v[228:231], v[170:173], v[96:99]
	v_mfma_f32_16x16x32_bf16 v[84:87], v[198:201], v[178:181], v[84:87]
	v_mfma_f32_16x16x32_bf16 v[80:83], v[228:231], v[178:181], v[80:83]
	v_mfma_f32_16x16x32_bf16 v[68:71], v[198:201], v[186:189], v[68:71]
	v_mfma_f32_16x16x32_bf16 v[64:67], v[228:231], v[186:189], v[64:67]
	s_mov_b32 m0, s68
	v_lshl_add_u64 v[206:207], s[8:9], 0, v[140:141]
	s_barrier
	ds_read_b128 v[158:161], v151 offset:16384
	ds_read_b128 v[162:165], v151 offset:17408
	ds_read_b128 v[166:169], v151 offset:18432
	ds_read_b128 v[170:173], v151 offset:19456
	ds_read_b128 v[174:177], v151 offset:20480
	ds_read_b128 v[178:181], v151 offset:21504
	ds_read_b128 v[182:185], v151 offset:22528
	ds_read_b128 v[186:189], v151 offset:23552
	global_load_lds_dwordx4 v[206:207], off
	v_lshl_add_u64 v[208:209], s[8:9], 0, v[138:139]
	s_mov_b32 m0, s71
	s_nop 0
	global_load_lds_dwordx4 v[208:209], off
	s_barrier
	s_waitcnt lgkmcnt(0)
	s_waitcnt lgkmcnt(0)
	v_mfma_f32_16x16x32_bf16 v[60:63], v[128:131], v[158:161], v[60:63]
	v_mfma_f32_16x16x32_bf16 v[56:59], v[146:149], v[158:161], v[56:59]
	v_mfma_f32_16x16x32_bf16 v[44:47], v[128:131], v[166:169], v[44:47]
	v_mfma_f32_16x16x32_bf16 v[40:43], v[146:149], v[166:169], v[40:43]
	v_mfma_f32_16x16x32_bf16 v[28:31], v[128:131], v[174:177], v[28:31]
	v_mfma_f32_16x16x32_bf16 v[24:27], v[146:149], v[174:177], v[24:27]
	v_mfma_f32_16x16x32_bf16 v[12:15], v[128:131], v[182:185], v[12:15]
	v_mfma_f32_16x16x32_bf16 v[8:11], v[146:149], v[182:185], v[8:11]
	v_mfma_f32_16x16x32_bf16 v[60:63], v[132:135], v[162:165], v[60:63]
	v_mfma_f32_16x16x32_bf16 v[56:59], v[154:157], v[162:165], v[56:59]
	v_mfma_f32_16x16x32_bf16 v[44:47], v[132:135], v[170:173], v[44:47]
	v_mfma_f32_16x16x32_bf16 v[40:43], v[154:157], v[170:173], v[40:43]
	v_mfma_f32_16x16x32_bf16 v[28:31], v[132:135], v[178:181], v[28:31]
	v_mfma_f32_16x16x32_bf16 v[24:27], v[154:157], v[178:181], v[24:27]
	v_mfma_f32_16x16x32_bf16 v[12:15], v[132:135], v[186:189], v[12:15]
	v_mfma_f32_16x16x32_bf16 v[8:11], v[154:157], v[186:189], v[8:11]
	s_barrier
; #define G_STAGE(bufoff, gbase) do { _Pragma("unroll") for (int _i = 0; _i < 2; ++_i) \
;     __builtin_amdgcn_global_load_lds((const unsigned*)((const char*)(gbase) + voffA[_i]), (LAS unsigned*)(lds + (bufoff) + ldsw + _i * 8192), 16, 0, 0); } while (0)
; #define G_LDA(dst, b, h) do { _Pragma("unroll") for (int m = 0; m < 4; ++m) _Pragma("unroll") for (int k = 0; k < 2; ++k) dst[m][k] = *(const LAS bf16x8*)(lds + G_SA(b, h) + aoff + m * 2048 + k * 1024); } while (0)
; #define G_LDB(dst, b, h) do { _Pragma("unroll") for (int n = 0; n < 2; ++n) _Pragma("unroll") for (int k = 0; k < 2; ++k) dst[n][k] = *(const LAS bf16x8*)(lds + G_SB(b, h) + boff + n * 2048 + k * 1024); } while (0)
; #define G_MMA(ai, bj, At, Bt) do { __builtin_amdgcn_s_setprio(1); _Pragma("unroll") for (int m = 0; m < 4; ++m) _Pragma("unroll") for (int n = 0; n < 2; ++n) _Pragma("unroll") for (int k = 0; k < 2; ++k) \
;     acc[ai][bj][m][n] = __builtin_amdgcn_mfma_f32_16x16x32_bf16(Bt[n][k], At[m][k], acc[ai][bj][m][n], 0, 0, 0); __builtin_amdgcn_s_setprio(0); } while (0)
; #define G_WAIT_V(n) asm volatile("s_waitcnt vmcnt(" #n ")" ::: "memory")
; #define G_WAIT_L(n) asm volatile("s_waitcnt lgkmcnt(" #n ")" ::: "memory")
; #define G_BAR __builtin_amdgcn_s_barrier()
; #define G_SCHED __builtin_amdgcn_sched_barrier(0)
; template <int MODE>
; __device__ __forceinline__ void gemm_phase(const Params& p, int layer, char* lds_generic) {
;     ...
;       G_WAIT_V(6); G_BAR; G_MMA(1, 1, At, B1); G_BAR;
;       G_LDB(B0, 1, 0); G_SCHED; G_LDA(At, 1, 0); G_STAGE(G_SA(0, 1), a2 + hstep);
;       G_WAIT_L(8); G_BAR; G_WAIT_L(0); G_MMA(0, 0, At, B0); G_BAR; G_SCHED;
;       G_LDB(B1, 1, 1); G_STAGE(G_SB(1, 0), b3);
;       G_BAR; G_WAIT_L(0); G_MMA(0, 1, At, B1); G_BAR;
;       G_LDA(At, 1, 1); G_STAGE(G_SA(1, 0), a3);
;       G_BAR; G_WAIT_L(0); G_MMA(1, 0, At, B0); G_BAR; G_SCHED;
	s_add_u32 s48, s6, 0x80000
	s_addc_u32 s49, s7, 0
	s_mov_b32 m0, s72
	v_lshl_add_u64 v[128:129], s[48:49], 0, v[140:141]
	global_load_lds_dwordx4 v[128:129], off
	v_lshl_add_u64 v[128:129], s[48:49], 0, v[138:139]
	s_mov_b32 m0, s73
	s_nop 0
	global_load_lds_dwordx4 v[128:129], off
	s_waitcnt vmcnt(6)
	s_barrier
	v_mfma_f32_16x16x32_bf16 v[52:55], v[194:197], v[158:161], v[52:55]
	v_mfma_f32_16x16x32_bf16 v[48:51], v[202:205], v[158:161], v[48:51]
	v_mfma_f32_16x16x32_bf16 v[36:39], v[194:197], v[166:169], v[36:39]
	v_mfma_f32_16x16x32_bf16 v[32:35], v[202:205], v[166:169], v[32:35]
	v_mfma_f32_16x16x32_bf16 v[20:23], v[194:197], v[174:177], v[20:23]
	v_mfma_f32_16x16x32_bf16 v[16:19], v[202:205], v[174:177], v[16:19]
	v_mfma_f32_16x16x32_bf16 v[4:7], v[194:197], v[182:185], v[4:7]
	v_mfma_f32_16x16x32_bf16 v[0:3], v[202:205], v[182:185], v[0:3]
	v_mfma_f32_16x16x32_bf16 v[52:55], v[198:201], v[162:165], v[52:55]
	v_mfma_f32_16x16x32_bf16 v[48:51], v[228:231], v[162:165], v[48:51]
	v_mfma_f32_16x16x32_bf16 v[36:39], v[198:201], v[170:173], v[36:39]
	v_mfma_f32_16x16x32_bf16 v[32:35], v[228:231], v[170:173], v[32:35]
	v_mfma_f32_16x16x32_bf16 v[20:23], v[198:201], v[178:181], v[20:23]
	v_mfma_f32_16x16x32_bf16 v[16:19], v[228:231], v[178:181], v[16:19]
	v_mfma_f32_16x16x32_bf16 v[4:7], v[198:201], v[186:189], v[4:7]
	v_mfma_f32_16x16x32_bf16 v[0:3], v[228:231], v[186:189], v[0:3]
	v_or_b32_e32 v128, 0x18000, v152
	v_add_u32_e32 v132, 0x18400, v152
	v_add_u32_e32 v146, 0x18800, v152
	v_add_u32_e32 v154, 0x18c00, v152
	s_barrier
	ds_read_b128 v[128:131], v128
	ds_read_b128 v[132:135], v132
	ds_read_b128 v[146:149], v146
	ds_read_b128 v[154:157], v154
	s_add_u32 s8, s8, 0x80000
	s_addc_u32 s9, s9, 0
	s_mov_b32 m0, s74
	v_lshl_add_u64 v[194:195], s[8:9], 0, v[140:141]
	ds_read_b128 v[158:161], v151 offset:32768
	ds_read_b128 v[162:165], v151 offset:33792
	ds_read_b128 v[166:169], v151 offset:34816
	ds_read_b128 v[170:173], v151 offset:35840
	ds_read_b128 v[174:177], v151 offset:36864
	ds_read_b128 v[178:181], v151 offset:37888
	ds_read_b128 v[182:185], v151 offset:38912
	ds_read_b128 v[186:189], v151 offset:39936
	global_load_lds_dwordx4 v[194:195], off
	v_lshl_add_u64 v[194:195], s[8:9], 0, v[138:139]
	s_mov_b32 m0, s75
	s_nop 0
	global_load_lds_dwordx4 v[194:195], off
	s_waitcnt lgkmcnt(8)
	s_barrier
	s_waitcnt lgkmcnt(0)
	s_waitcnt lgkmcnt(0)
	v_mfma_f32_16x16x32_bf16 v[124:127], v[128:131], v[158:161], v[124:127]
	v_mfma_f32_16x16x32_bf16 v[120:123], v[146:149], v[158:161], v[120:123]
	v_mfma_f32_16x16x32_bf16 v[108:111], v[128:131], v[166:169], v[108:111]
	v_mfma_f32_16x16x32_bf16 v[104:107], v[146:149], v[166:169], v[104:107]
	v_mfma_f32_16x16x32_bf16 v[92:95], v[128:131], v[174:177], v[92:95]
	v_mfma_f32_16x16x32_bf16 v[88:91], v[146:149], v[174:177], v[88:91]
	v_mfma_f32_16x16x32_bf16 v[76:79], v[128:131], v[182:185], v[76:79]
	v_mfma_f32_16x16x32_bf16 v[72:75], v[146:149], v[182:185], v[72:75]
	v_mfma_f32_16x16x32_bf16 v[124:127], v[132:135], v[162:165], v[124:127]
	v_mfma_f32_16x16x32_bf16 v[120:123], v[154:157], v[162:165], v[120:123]
	v_mfma_f32_16x16x32_bf16 v[108:111], v[132:135], v[170:173], v[108:111]
	v_mfma_f32_16x16x32_bf16 v[104:107], v[154:157], v[170:173], v[104:107]
	v_mfma_f32_16x16x32_bf16 v[92:95], v[132:135], v[178:181], v[92:95]
	v_mfma_f32_16x16x32_bf16 v[88:91], v[154:157], v[178:181], v[88:91]
	v_mfma_f32_16x16x32_bf16 v[76:79], v[132:135], v[186:189], v[76:79]
	v_mfma_f32_16x16x32_bf16 v[72:75], v[154:157], v[186:189], v[72:75]
	s_barrier
	s_mov_b32 m0, s77
	v_or_b32_e32 v194, 0x1c000, v152
	v_add_u32_e32 v198, 0x1c400, v152
	v_add_u32_e32 v202, 0x1c800, v152
	v_lshl_add_u64 v[136:137], v[136:137], 0, s[90:91]
	ds_read_b128 v[194:197], v194
	ds_read_b128 v[198:201], v198
	v_add_u32_e32 v210, 0x1cc00, v152
	ds_read_b128 v[202:205], v202
	ds_read_b128 v[228:231], v210
	global_load_lds_dwordx4 v[136:137], off
	v_lshl_add_u64 v[136:137], v[190:191], 0, s[90:91]
	s_mov_b32 m0, s78
	s_nop 0
	global_load_lds_dwordx4 v[136:137], off
	s_barrier
	s_waitcnt lgkmcnt(0)
	s_waitcnt lgkmcnt(0)
	v_mfma_f32_16x16x32_bf16 v[116:119], v[194:197], v[158:161], v[116:119]
	v_mfma_f32_16x16x32_bf16 v[112:115], v[202:205], v[158:161], v[112:115]
	v_mfma_f32_16x16x32_bf16 v[100:103], v[194:197], v[166:169], v[100:103]
	v_mfma_f32_16x16x32_bf16 v[96:99], v[202:205], v[166:169], v[96:99]
	v_mfma_f32_16x16x32_bf16 v[84:87], v[194:197], v[174:177], v[84:87]
	v_mfma_f32_16x16x32_bf16 v[80:83], v[202:205], v[174:177], v[80:83]
	v_mfma_f32_16x16x32_bf16 v[68:71], v[194:197], v[182:185], v[68:71]
	v_mfma_f32_16x16x32_bf16 v[64:67], v[202:205], v[182:185], v[64:67]
	v_mfma_f32_16x16x32_bf16 v[116:119], v[198:201], v[162:165], v[116:119]
	v_mfma_f32_16x16x32_bf16 v[112:115], v[228:231], v[162:165], v[112:115]
	v_mfma_f32_16x16x32_bf16 v[100:103], v[198:201], v[170:173], v[100:103]
	v_mfma_f32_16x16x32_bf16 v[96:99], v[228:231], v[170:173], v[96:99]
	v_mfma_f32_16x16x32_bf16 v[84:87], v[198:201], v[178:181], v[84:87]
	v_mfma_f32_16x16x32_bf16 v[80:83], v[228:231], v[178:181], v[80:83]
	v_mfma_f32_16x16x32_bf16 v[68:71], v[198:201], v[186:189], v[68:71]
	v_mfma_f32_16x16x32_bf16 v[64:67], v[228:231], v[186:189], v[64:67]
	s_mov_b32 m0, s79
	v_lshl_add_u64 v[136:137], v[206:207], 0, s[90:91]
	s_barrier
	ds_read_b128 v[158:161], v151 offset:49152
	ds_read_b128 v[162:165], v151 offset:50176
	ds_read_b128 v[166:169], v151 offset:51200
	ds_read_b128 v[170:173], v151 offset:52224
	ds_read_b128 v[174:177], v151 offset:53248
	ds_read_b128 v[178:181], v151 offset:54272
	ds_read_b128 v[182:185], v151 offset:55296
	ds_read_b128 v[186:189], v151 offset:56320
	global_load_lds_dwordx4 v[136:137], off
	v_lshl_add_u64 v[136:137], v[208:209], 0, s[90:91]
	s_mov_b32 m0, s86
	s_nop 0
	global_load_lds_dwordx4 v[136:137], off
	s_barrier
;   __device__ __forceinline__ bf16_t* Z() const { return (bf16_t*)(ws + 456 * MB); }
;   __device__ __forceinline__ float* cosT() const { return (float*)(ws + 904 * MB); }
;   __device__ __forceinline__ float* sinT() const { return (float*)(ws + 905 * MB); }
;   __device__ __forceinline__ float* RS() const { return (float*)(ws + 906 * MB); }
; #define G_STAGE(bufoff, gbase) do { _Pragma("unroll") for (int _i = 0; _i < 2; ++_i) \
;     __builtin_amdgcn_global_load_lds((const unsigned*)((const char*)(gbase) + voffA[_i]), (LAS unsigned*)(lds + (bufoff) + ldsw + _i * 8192), 16, 0, 0); } while (0)
; #define G_WAIT_V(n) asm volatile("s_waitcnt vmcnt(" #n ")" ::: "memory")
; #define G_WAIT_L(n) asm volatile("s_waitcnt lgkmcnt(" #n ")" ::: "memory")
; template <int MODE>
; __device__ __forceinline__ void gemm_epilogue(const Params& p, int layer, const f32x4 (&acc)[2][2][4][2], int pm, int pn, int wr, int wc, int fr, int fq) {
;     ...
;       const int row = pm * 256 + ai * 128 + wr * 64 + m * 16 + fr;
;       if (MODE == 0) {
;         const float rsv = p.RS()[row];
;         const int pos = (row < NPROMPT) ? (row & 8191) : (row & 4095);
; #pragma unroll
;         for (int bj = 0; bj < 2; ++bj) {
;           const int colt = pn * 256 + bj * 128 + wc * 32;
;           f32x4 v0 = acc[ai][bj][m][0] * rsv, v1 = acc[ai][bj][m][1] * rsv;
;           bf16_t* zp = p.Z() + (size_t)row * LDZ + colt;
;           if (colt < 2048) {
;             const int ti = pos * 32 + 16 * (wc & 1) + 4 * fq;
;             const f32x4 c = *(const f32x4*)(p.cosT() + ti), s = *(const f32x4*)(p.sinT() + ti);
;             const float qs = (colt < 1024) ? 0.18033688011112042f : 1.f;
;             const f32x4 o0 = (v0 * c - v1 * s) * qs, o1 = (v1 * c + v0 * s) * qs;
;             const u32x4 w = {cvtpk(o0[0], o0[1]), cvtpk(o0[2], o0[3]), cvtpk(o1[0], o1[1]), cvtpk(o1[2], o1[3])};
;             *(u32x4*)(zp + 8 * fq) = w;
;           } else {
;             if (colt >= 3072) {
; #pragma unroll
;               for (int e = 0; e < 4; ++e) { v0[e] = gelu_tanh(v0[e]); v1[e] = gelu_tanh(v1[e]); }
;             }
; template <int MODE>
; __device__ __forceinline__ void gemm_phase(const Params& p, int layer, char* lds_generic) {
;     ...
;       G_BAR; G_WAIT_L(0); G_MMA(1, 0, At, B0); G_BAR; G_SCHED;
;       G_STAGE(G_SB(1, 1), b3 + hstep);
;       G_WAIT_V(6); G_BAR; G_MMA(1, 1, At, B1); G_BAR;
;     }
	s_waitcnt lgkmcnt(0)
	s_waitcnt lgkmcnt(0)
	v_mfma_f32_16x16x32_bf16 v[60:63], v[128:131], v[158:161], v[60:63]
	v_mfma_f32_16x16x32_bf16 v[56:59], v[146:149], v[158:161], v[56:59]
	v_mfma_f32_16x16x32_bf16 v[44:47], v[128:131], v[166:169], v[44:47]
	v_mfma_f32_16x16x32_bf16 v[40:43], v[146:149], v[166:169], v[40:43]
	v_mfma_f32_16x16x32_bf16 v[28:31], v[128:131], v[174:177], v[28:31]
	v_mfma_f32_16x16x32_bf16 v[24:27], v[146:149], v[174:177], v[24:27]
	v_mfma_f32_16x16x32_bf16 v[12:15], v[128:131], v[182:185], v[12:15]
	v_mfma_f32_16x16x32_bf16 v[8:11], v[146:149], v[182:185], v[8:11]
	v_mfma_f32_16x16x32_bf16 v[60:63], v[132:135], v[162:165], v[60:63]
	v_mfma_f32_16x16x32_bf16 v[56:59], v[154:157], v[162:165], v[56:59]
	v_mfma_f32_16x16x32_bf16 v[44:47], v[132:135], v[170:173], v[44:47]
	v_mfma_f32_16x16x32_bf16 v[40:43], v[154:157], v[170:173], v[40:43]
	v_mfma_f32_16x16x32_bf16 v[28:31], v[132:135], v[178:181], v[28:31]
	v_mfma_f32_16x16x32_bf16 v[24:27], v[154:157], v[178:181], v[24:27]
	v_mfma_f32_16x16x32_bf16 v[12:15], v[132:135], v[186:189], v[12:15]
	v_mfma_f32_16x16x32_bf16 v[8:11], v[154:157], v[186:189], v[8:11]
	s_barrier
	s_add_u32 s6, s6, 0x80080
	s_addc_u32 s7, s7, 0
	s_mov_b32 m0, s87
	v_lshl_add_u64 v[128:129], s[6:7], 0, v[140:141]
	global_load_lds_dwordx4 v[128:129], off
	v_lshl_add_u64 v[128:129], s[6:7], 0, v[138:139]
	s_mov_b32 m0, s88
	s_nop 0
	global_load_lds_dwordx4 v[128:129], off
	s_waitcnt vmcnt(6)
	s_barrier
	v_mfma_f32_16x16x32_bf16 v[52:55], v[194:197], v[158:161], v[52:55]
	v_mfma_f32_16x16x32_bf16 v[48:51], v[202:205], v[158:161], v[48:51]
	v_mfma_f32_16x16x32_bf16 v[36:39], v[194:197], v[166:169], v[36:39]
	v_mfma_f32_16x16x32_bf16 v[32:35], v[202:205], v[166:169], v[32:35]
	v_mfma_f32_16x16x32_bf16 v[20:23], v[194:197], v[174:177], v[20:23]
	v_mfma_f32_16x16x32_bf16 v[16:19], v[202:205], v[174:177], v[16:19]
	v_mfma_f32_16x16x32_bf16 v[4:7], v[194:197], v[182:185], v[4:7]
	v_mfma_f32_16x16x32_bf16 v[0:3], v[202:205], v[182:185], v[0:3]
	v_mfma_f32_16x16x32_bf16 v[52:55], v[198:201], v[162:165], v[52:55]
	v_mfma_f32_16x16x32_bf16 v[48:51], v[228:231], v[162:165], v[48:51]
	v_mfma_f32_16x16x32_bf16 v[36:39], v[198:201], v[170:173], v[36:39]
	v_mfma_f32_16x16x32_bf16 v[32:35], v[228:231], v[170:173], v[32:35]
	v_mfma_f32_16x16x32_bf16 v[20:23], v[198:201], v[178:181], v[20:23]
	v_mfma_f32_16x16x32_bf16 v[16:19], v[228:231], v[178:181], v[16:19]
	v_mfma_f32_16x16x32_bf16 v[4:7], v[198:201], v[186:189], v[4:7]
	v_mfma_f32_16x16x32_bf16 v[0:3], v[228:231], v[186:189], v[0:3]
	s_add_i32 s47, s47, 2
	s_add_u32 s4, s4, 0x100
	s_addc_u32 s5, s5, 0
	s_add_u32 s35, s35, 0x100
	s_addc_u32 s46, s46, 0
	s_cmp_gt_u32 s47, 29
	s_barrier
	s_cbranch_scc0 .LBB0_196
	v_lshl_add_u32 v146, s1, 8, v150
	v_ashrrev_i32_e32 v147, 31, v146
	v_lshl_add_u64 v[128:129], v[146:147], 2, s[12:13]
	global_load_dword v148, v[128:129], off
	global_load_dword v243, v[128:129], off offset:64
	global_load_dword v244, v[128:129], off offset:128
	global_load_dword v245, v[128:129], off offset:192
	global_load_dword v246, v[128:129], off offset:512
	global_load_dword v247, v[128:129], off offset:576
	global_load_dword v248, v[128:129], off offset:640
	global_load_dword v249, v[128:129], off offset:704
	s_lshl_b32 s1, s33, 8
	s_or_b32 s46, s1, s76
	s_cmpk_gt_i32 s46, 0x7ff
	s_movk_i32 s2, 0x4000
	s_cselect_b64 s[8:9], -1, 0
	v_cmp_gt_i32_e64 s[4:5], s2, v146
	s_mov_b64 s[6:7], -1
	s_and_b64 vcc, exec, s[8:9]
	s_waitcnt vmcnt(0)
	v_pk_mul_f32 v[126:127], v[126:127], v[148:149] op_sel_hi:[1,0]
	v_pk_mul_f32 v[124:125], v[124:125], v[148:149] op_sel_hi:[1,0]
	v_pk_mul_f32 v[122:123], v[122:123], v[148:149] op_sel_hi:[1,0]
	v_pk_mul_f32 v[120:121], v[120:121], v[148:149] op_sel_hi:[1,0]
	s_cbranch_vccz .LBB0_201
	v_mov_b64_e32 v[132:133], v[122:123]
	v_mov_b64_e32 v[136:137], v[126:127]
	s_cmpk_lt_u32 s1, 0xc00
	v_mov_b64_e32 v[130:131], v[120:121]
	v_mov_b64_e32 v[134:135], v[124:125]
	s_cbranch_scc1 .LBB0_200
	v_mul_f32_e32 v129, v120, v120
	v_fmamk_f32 v129, v129, 0x3dd2d3e8, v214
	v_mul_f32_e32 v130, v125, v125
	v_mul_f32_e64 v129, v120, -v129
	v_fmamk_f32 v130, v130, 0x3dd2d3e8, v214
	v_exp_f32_e32 v129, v129
	v_mul_f32_e64 v130, v125, -v130
	v_exp_f32_e32 v131, v130
	v_mul_f32_e32 v133, v122, v122
	v_add_f32_e32 v129, 1.0, v129
	v_mul_f32_e32 v128, v124, v124
	v_rcp_f32_e32 v130, v129
	v_add_f32_e32 v129, 1.0, v131
	v_mul_f32_e32 v131, v121, v121
	v_mul_f32_e32 v132, v126, v126
	v_fmamk_f32 v133, v133, 0x3dd2d3e8, v214
	v_mul_f32_e32 v134, v127, v127
	v_mul_f32_e32 v135, v123, v123
	v_fmamk_f32 v128, v128, 0x3dd2d3e8, v214
	v_fmamk_f32 v131, v131, 0x3dd2d3e8, v214
	v_fmamk_f32 v132, v132, 0x3dd2d3e8, v214
	v_mul_f32_e64 v133, v122, -v133
	v_fmamk_f32 v134, v134, 0x3dd2d3e8, v214
	v_fmamk_f32 v135, v135, 0x3dd2d3e8, v214
	v_mul_f32_e64 v128, v124, -v128
	v_mul_f32_e64 v131, v121, -v131
	v_mul_f32_e64 v132, v126, -v132
	v_exp_f32_e32 v133, v133
	v_mul_f32_e64 v134, v127, -v134
	v_mul_f32_e64 v135, v123, -v135
	v_exp_f32_e32 v128, v128
	v_exp_f32_e32 v131, v131
	v_exp_f32_e32 v132, v132
	v_exp_f32_e32 v134, v134
	v_exp_f32_e32 v135, v135
	v_add_f32_e32 v133, 1.0, v133
	v_add_f32_e32 v128, 1.0, v128
	v_add_f32_e32 v131, 1.0, v131
	v_add_f32_e32 v132, 1.0, v132
	v_rcp_f32_e32 v154, v133
	v_add_f32_e32 v133, 1.0, v134
	v_add_f32_e32 v134, 1.0, v135
	v_rcp_f32_e32 v128, v128
	v_rcp_f32_e32 v129, v129
	v_rcp_f32_e32 v132, v132
	v_rcp_f32_e32 v133, v133
	v_rcp_f32_e32 v155, v134
	v_rcp_f32_e32 v131, v131
	v_pk_mul_f32 v[134:135], v[124:125], v[128:129]
	v_pk_mul_f32 v[136:137], v[126:127], v[132:133]
	v_pk_mul_f32 v[132:133], v[122:123], v[154:155]
	v_pk_mul_f32 v[130:131], v[120:121], v[130:131]
